# prep-load-hoisting-and-peeled-last-gemm-iteration-no-redundant-tail-loads
# speedup vs baseline: 1.1745x; 1.0083x over previous
.LBB0_78:
	s_or_b64 exec, exec, s[0:1]
	v_and_b32_e32 v2, 1, v32
	s_lshl_b32 s3, s3, 4
	v_ashrrev_i32_e32 v8, 7, v32
	v_cmp_eq_u32_e32 vcc, 0, v2
	v_add_u32_e32 v2, s3, v8
	v_ashrrev_i32_e32 v3, 31, v2
	v_lshlrev_b64 v[2:3], 8, v[2:3]
	v_and_b32_e32 v4, 0xfc, v5
	v_or_b32_e32 v2, v2, v4
	v_lshl_add_u64 v[6:7], s[64:65], 0, v[2:3]
	v_lshl_add_u64 v[2:3], s[66:67], 0, v[2:3]
	s_waitcnt lgkmcnt(0)
	s_barrier
	global_load_dword v16, v[2:3], off
	global_load_dword v17, v[6:7], off
	v_add_u32_e32 v11, 0x100, v32
	v_ashrrev_i32_e32 v11, 7, v11
	v_add_u32_e32 v12, s3, v11
	v_ashrrev_i32_e32 v13, 31, v12
	v_lshlrev_b64 v[12:13], 8, v[12:13]
	v_or_b32_e32 v12, v12, v4
	v_lshl_add_u64 v[12:13], s[66:67], 0, v[12:13]
	global_load_dword v18, v[12:13], off
	v_add_u32_e32 v11, 0x100, v32
	v_ashrrev_i32_e32 v11, 7, v11
	v_add_u32_e32 v12, s3, v11
	v_ashrrev_i32_e32 v13, 31, v12
	v_lshlrev_b64 v[12:13], 8, v[12:13]
	v_or_b32_e32 v12, v12, v4
	v_lshl_add_u64 v[14:15], s[64:65], 0, v[12:13]
	global_load_dword v19, v[14:15], off
	v_add_u32_e32 v11, 0x200, v32
	v_ashrrev_i32_e32 v11, 7, v11
	v_add_u32_e32 v12, s3, v11
	v_ashrrev_i32_e32 v13, 31, v12
	v_lshlrev_b64 v[12:13], 8, v[12:13]
	v_or_b32_e32 v12, v12, v4
	v_lshl_add_u64 v[12:13], s[66:67], 0, v[12:13]
	global_load_dword v20, v[12:13], off
	v_add_u32_e32 v11, 0x200, v32
	v_ashrrev_i32_e32 v11, 7, v11
	v_add_u32_e32 v12, s3, v11
	v_ashrrev_i32_e32 v13, 31, v12
	v_lshlrev_b64 v[12:13], 8, v[12:13]
	v_or_b32_e32 v12, v12, v4
	v_lshl_add_u64 v[14:15], s[64:65], 0, v[12:13]
	global_load_dword v21, v[14:15], off
	v_add_u32_e32 v11, 0x300, v32
	v_ashrrev_i32_e32 v11, 7, v11
	v_add_u32_e32 v12, s3, v11
	v_ashrrev_i32_e32 v13, 31, v12
	v_lshlrev_b64 v[12:13], 8, v[12:13]
	v_or_b32_e32 v12, v12, v4
	v_lshl_add_u64 v[12:13], s[66:67], 0, v[12:13]
	global_load_dword v22, v[12:13], off
	v_add_u32_e32 v11, 0x300, v32
	v_ashrrev_i32_e32 v11, 7, v11
	v_add_u32_e32 v12, s3, v11
	v_ashrrev_i32_e32 v13, 31, v12
	v_lshlrev_b64 v[12:13], 8, v[12:13]
	v_or_b32_e32 v12, v12, v4
	v_lshl_add_u64 v[14:15], s[64:65], 0, v[12:13]
	global_load_dword v23, v[14:15], off
	v_add_u32_e32 v11, 0x400, v32
	v_ashrrev_i32_e32 v11, 7, v11
	v_add_u32_e32 v12, s3, v11
	v_ashrrev_i32_e32 v13, 31, v12
	v_lshlrev_b64 v[12:13], 8, v[12:13]
	v_or_b32_e32 v12, v12, v4
	v_lshl_add_u64 v[12:13], s[66:67], 0, v[12:13]
	global_load_dword v24, v[12:13], off
	v_add_u32_e32 v11, 0x400, v32
	v_ashrrev_i32_e32 v11, 7, v11
	v_add_u32_e32 v12, s3, v11
	v_ashrrev_i32_e32 v13, 31, v12
	v_lshlrev_b64 v[12:13], 8, v[12:13]
	v_or_b32_e32 v12, v12, v4
	v_lshl_add_u64 v[14:15], s[64:65], 0, v[12:13]
	global_load_dword v25, v[14:15], off
	v_add_u32_e32 v11, 0x500, v32
	v_ashrrev_i32_e32 v11, 7, v11
	v_add_u32_e32 v12, s3, v11
	v_ashrrev_i32_e32 v13, 31, v12
	v_lshlrev_b64 v[12:13], 8, v[12:13]
	v_or_b32_e32 v12, v12, v4
	v_lshl_add_u64 v[12:13], s[66:67], 0, v[12:13]
	global_load_dword v26, v[12:13], off
	v_add_u32_e32 v11, 0x500, v32
	v_ashrrev_i32_e32 v11, 7, v11
	v_add_u32_e32 v12, s3, v11
	v_ashrrev_i32_e32 v13, 31, v12
	v_lshlrev_b64 v[12:13], 8, v[12:13]
	v_or_b32_e32 v12, v12, v4
	v_lshl_add_u64 v[14:15], s[64:65], 0, v[12:13]
	global_load_dword v27, v[14:15], off
	v_add_u32_e32 v11, 0x600, v32
	v_ashrrev_i32_e32 v11, 7, v11
	v_add_u32_e32 v12, s3, v11
	v_ashrrev_i32_e32 v13, 31, v12
	v_lshlrev_b64 v[12:13], 8, v[12:13]
	v_or_b32_e32 v12, v12, v4
	v_lshl_add_u64 v[12:13], s[66:67], 0, v[12:13]
	global_load_dword v28, v[12:13], off
	v_add_u32_e32 v11, 0x600, v32
	v_ashrrev_i32_e32 v11, 7, v11
	v_add_u32_e32 v12, s3, v11
	v_ashrrev_i32_e32 v13, 31, v12
	v_lshlrev_b64 v[12:13], 8, v[12:13]
	v_or_b32_e32 v12, v12, v4
	v_lshl_add_u64 v[14:15], s[64:65], 0, v[12:13]
	global_load_dword v29, v[14:15], off
	v_add_u32_e32 v11, 0x700, v32
	v_ashrrev_i32_e32 v14, 7, v11
	v_add_u32_e32 v12, s3, v14
	v_ashrrev_i32_e32 v13, 31, v12
	v_lshlrev_b64 v[12:13], 8, v[12:13]
	v_or_b32_e32 v12, v12, v4
	v_lshl_add_u64 v[10:11], s[64:65], 0, v[12:13]
	global_load_dword v30, v[10:11], off
	v_add_u32_e32 v11, 0x700, v32
	v_ashrrev_i32_e32 v14, 7, v11
	v_add_u32_e32 v12, s3, v14
	v_ashrrev_i32_e32 v13, 31, v12
	v_lshlrev_b64 v[12:13], 8, v[12:13]
	v_or_b32_e32 v12, v12, v4
	v_lshl_add_u64 v[10:11], s[66:67], 0, v[12:13]
	global_load_dword v31, v[10:11], off
	s_waitcnt vmcnt(0)
	v_mov_b32_e32 v2, v16
	v_and_b32_e32 v0, 0x7e, v32
	v_mov_b32_e32 v6, v17
	v_lshlrev_b32_e32 v0, 2, v0
	ds_read_b64 v[0:1], v0
	s_lshl_b32 s0, s5, 9
	s_lshl_b32 s1, s2, 4
	s_or_b32 s2, s0, s1
	s_lshl_b32 s78, s4, 8
	v_and_b32_e32 v192, 0xfe, v5
	s_mov_b32 s4, 0x1648000
	v_add_u32_e32 v5, 0x100, v32
	v_ashrrev_i32_e32 v5, 7, v5
	s_waitcnt lgkmcnt(0)
	v_mul_f32_e32 v3, v1, v2
	v_mul_f32_e32 v2, v0, v2
	v_fma_f32 v3, v0, v6, -v3
	v_fmac_f32_e32 v2, v1, v6
	v_cndmask_b32_e64 v2, -v2, v3, vcc
	v_bfe_u32 v3, v2, 16, 1
	v_add3_u32 v9, v2, v3, s80
	v_add_u32_e32 v6, s2, v8
	v_mov_b64_e32 v[2:3], s[90:91]
	v_mad_i64_i32 v[6:7], s[0:1], v6, s68, v[2:3]
	v_lshl_add_u64 v[6:7], v[6:7], 0, s[78:79]
	v_lshl_add_u64 v[6:7], v[6:7], 0, v[192:193]
	v_add_co_u32_e64 v6, s[0:1], s4, v6
	s_nop 1
	v_addc_co_u32_e64 v7, s[0:1], 0, v7, s[0:1]
	global_store_short_d16_hi v[6:7], v9, off offset:1024
	v_add_u32_e32 v6, s3, v5
	v_ashrrev_i32_e32 v7, 31, v6
	v_lshlrev_b64 v[6:7], 8, v[6:7]
	v_or_b32_e32 v6, v6, v4
	v_lshl_add_u64 v[8:9], s[64:65], 0, v[6:7]
	v_lshl_add_u64 v[6:7], s[66:67], 0, v[6:7]
	v_mov_b32_e32 v6, v18
	v_add_u32_e32 v5, s2, v5
	v_mov_b32_e32 v8, v19
	v_mul_f32_e32 v7, v1, v6
	v_mul_f32_e32 v6, v0, v6
	v_fma_f32 v7, v0, v8, -v7
	v_fmac_f32_e32 v6, v1, v8
	v_cndmask_b32_e64 v6, -v6, v7, vcc
	v_bfe_u32 v7, v6, 16, 1
	v_add3_u32 v8, v6, v7, s80
	v_mad_i64_i32 v[6:7], s[0:1], v5, s68, v[2:3]
	v_lshl_add_u64 v[6:7], v[6:7], 0, s[78:79]
	v_lshl_add_u64 v[6:7], v[6:7], 0, v[192:193]
	v_add_co_u32_e64 v6, s[0:1], s4, v6
	v_add_u32_e32 v5, 0x200, v32
	s_nop 0
	v_addc_co_u32_e64 v7, s[0:1], 0, v7, s[0:1]
	v_ashrrev_i32_e32 v5, 7, v5
	global_store_short_d16_hi v[6:7], v8, off offset:1024
	v_add_u32_e32 v6, s3, v5
	v_ashrrev_i32_e32 v7, 31, v6
	v_lshlrev_b64 v[6:7], 8, v[6:7]
	v_or_b32_e32 v6, v6, v4
	v_lshl_add_u64 v[8:9], s[64:65], 0, v[6:7]
	v_lshl_add_u64 v[6:7], s[66:67], 0, v[6:7]
	v_mov_b32_e32 v6, v20
	v_add_u32_e32 v5, s2, v5
	v_mov_b32_e32 v8, v21
	v_mul_f32_e32 v7, v1, v6
	v_mul_f32_e32 v6, v0, v6
	v_fma_f32 v7, v0, v8, -v7
	v_fmac_f32_e32 v6, v1, v8
	v_cndmask_b32_e64 v6, -v6, v7, vcc
	v_bfe_u32 v7, v6, 16, 1
	v_add3_u32 v8, v6, v7, s80
	v_mad_i64_i32 v[6:7], s[0:1], v5, s68, v[2:3]
	v_lshl_add_u64 v[6:7], v[6:7], 0, s[78:79]
	v_lshl_add_u64 v[6:7], v[6:7], 0, v[192:193]
	v_add_co_u32_e64 v6, s[0:1], s4, v6
	v_add_u32_e32 v5, 0x300, v32
	s_nop 0
	v_addc_co_u32_e64 v7, s[0:1], 0, v7, s[0:1]
	v_ashrrev_i32_e32 v5, 7, v5
	global_store_short_d16_hi v[6:7], v8, off offset:1024
	v_add_u32_e32 v6, s3, v5
	v_ashrrev_i32_e32 v7, 31, v6
	v_lshlrev_b64 v[6:7], 8, v[6:7]
	v_or_b32_e32 v6, v6, v4
	v_lshl_add_u64 v[8:9], s[64:65], 0, v[6:7]
	v_lshl_add_u64 v[6:7], s[66:67], 0, v[6:7]
	v_mov_b32_e32 v6, v22
	v_add_u32_e32 v5, s2, v5
	v_mov_b32_e32 v8, v23
	v_mul_f32_e32 v7, v1, v6
	v_mul_f32_e32 v6, v0, v6
	v_fma_f32 v7, v0, v8, -v7
	v_fmac_f32_e32 v6, v1, v8
	v_cndmask_b32_e64 v6, -v6, v7, vcc
	v_bfe_u32 v7, v6, 16, 1
	v_add3_u32 v8, v6, v7, s80
	v_mad_i64_i32 v[6:7], s[0:1], v5, s68, v[2:3]
	v_lshl_add_u64 v[6:7], v[6:7], 0, s[78:79]
	v_lshl_add_u64 v[6:7], v[6:7], 0, v[192:193]
	v_add_co_u32_e64 v6, s[0:1], s4, v6
	v_add_u32_e32 v5, 0x400, v32
	s_nop 0
	v_addc_co_u32_e64 v7, s[0:1], 0, v7, s[0:1]
	v_ashrrev_i32_e32 v5, 7, v5
	global_store_short_d16_hi v[6:7], v8, off offset:1024
	v_add_u32_e32 v6, s3, v5
	v_ashrrev_i32_e32 v7, 31, v6
	v_lshlrev_b64 v[6:7], 8, v[6:7]
	v_or_b32_e32 v6, v6, v4
	v_lshl_add_u64 v[8:9], s[64:65], 0, v[6:7]
	v_lshl_add_u64 v[6:7], s[66:67], 0, v[6:7]
	v_mov_b32_e32 v6, v24
	v_add_u32_e32 v5, s2, v5
	v_mov_b32_e32 v8, v25
	v_mul_f32_e32 v7, v1, v6
	v_mul_f32_e32 v6, v0, v6
	v_fma_f32 v7, v0, v8, -v7
	v_fmac_f32_e32 v6, v1, v8
	v_cndmask_b32_e64 v6, -v6, v7, vcc
	v_bfe_u32 v7, v6, 16, 1
	v_add3_u32 v8, v6, v7, s80
	v_mad_i64_i32 v[6:7], s[0:1], v5, s68, v[2:3]
	v_lshl_add_u64 v[6:7], v[6:7], 0, s[78:79]
	v_lshl_add_u64 v[6:7], v[6:7], 0, v[192:193]
	v_add_co_u32_e64 v6, s[0:1], s4, v6
	v_add_u32_e32 v5, 0x500, v32
	s_nop 0
	v_addc_co_u32_e64 v7, s[0:1], 0, v7, s[0:1]
	v_ashrrev_i32_e32 v5, 7, v5
	global_store_short_d16_hi v[6:7], v8, off offset:1024
	v_add_u32_e32 v6, s3, v5
	v_ashrrev_i32_e32 v7, 31, v6
	v_lshlrev_b64 v[6:7], 8, v[6:7]
	v_or_b32_e32 v6, v6, v4
	v_lshl_add_u64 v[8:9], s[64:65], 0, v[6:7]
	v_lshl_add_u64 v[6:7], s[66:67], 0, v[6:7]
	v_mov_b32_e32 v6, v26
	v_add_u32_e32 v5, s2, v5
	v_mov_b32_e32 v8, v27
	v_mul_f32_e32 v7, v1, v6
	v_mul_f32_e32 v6, v0, v6
	v_fma_f32 v7, v0, v8, -v7
	v_fmac_f32_e32 v6, v1, v8
	v_cndmask_b32_e64 v6, -v6, v7, vcc
	v_bfe_u32 v7, v6, 16, 1
	v_add3_u32 v8, v6, v7, s80
	v_mad_i64_i32 v[6:7], s[0:1], v5, s68, v[2:3]
	v_lshl_add_u64 v[6:7], v[6:7], 0, s[78:79]
	v_lshl_add_u64 v[6:7], v[6:7], 0, v[192:193]
	v_add_co_u32_e64 v6, s[0:1], s4, v6
	v_add_u32_e32 v5, 0x600, v32
	s_nop 0
	v_addc_co_u32_e64 v7, s[0:1], 0, v7, s[0:1]
	v_ashrrev_i32_e32 v5, 7, v5
	global_store_short_d16_hi v[6:7], v8, off offset:1024
	v_add_u32_e32 v6, s3, v5
	v_ashrrev_i32_e32 v7, 31, v6
	v_lshlrev_b64 v[6:7], 8, v[6:7]
	v_or_b32_e32 v6, v6, v4
	v_lshl_add_u64 v[8:9], s[64:65], 0, v[6:7]
	v_lshl_add_u64 v[6:7], s[66:67], 0, v[6:7]
	v_mov_b32_e32 v6, v28
	v_add_u32_e32 v5, s2, v5
	v_mov_b32_e32 v8, v29
	v_mul_f32_e32 v7, v1, v6
	v_mul_f32_e32 v6, v0, v6
	v_fma_f32 v7, v0, v8, -v7
	v_fmac_f32_e32 v6, v1, v8
	v_cndmask_b32_e64 v6, -v6, v7, vcc
	v_bfe_u32 v7, v6, 16, 1
	v_add3_u32 v8, v6, v7, s80
	v_mad_i64_i32 v[6:7], s[0:1], v5, s68, v[2:3]
	v_lshl_add_u64 v[6:7], v[6:7], 0, s[78:79]
	v_lshl_add_u64 v[6:7], v[6:7], 0, v[192:193]
	v_add_co_u32_e64 v6, s[0:1], s4, v6
	v_add_u32_e32 v5, 0x700, v32
	s_nop 0
	v_addc_co_u32_e64 v7, s[0:1], 0, v7, s[0:1]
	global_store_short_d16_hi v[6:7], v8, off offset:1024
	v_ashrrev_i32_e32 v8, 7, v5
	v_add_u32_e32 v6, s3, v8
	v_ashrrev_i32_e32 v7, 31, v6
	v_lshlrev_b64 v[6:7], 8, v[6:7]
	v_or_b32_e32 v6, v6, v4
	v_lshl_add_u64 v[4:5], s[64:65], 0, v[6:7]
	v_mov_b32_e32 v9, v30
	v_lshl_add_u64 v[4:5], s[66:67], 0, v[6:7]
	v_mov_b32_e32 v4, v31
	v_mul_f32_e32 v5, v1, v4
	v_fma_f32 v5, v0, v9, -v5
	v_mul_f32_e32 v0, v0, v4
	v_fmac_f32_e32 v0, v1, v9
	v_cndmask_b32_e64 v0, -v0, v5, vcc
	v_bfe_u32 v1, v0, 16, 1
	v_add3_u32 v4, v0, v1, s80
	v_add_u32_e32 v0, s2, v8
	v_mad_i64_i32 v[0:1], s[0:1], v0, s68, v[2:3]
	v_lshl_add_u64 v[0:1], v[0:1], 0, s[78:79]
	v_lshl_add_u64 v[0:1], v[0:1], 0, v[192:193]
	v_add_co_u32_e32 v0, vcc, 0x1648000, v0
	s_nop 1
	v_addc_co_u32_e32 v1, vcc, 0, v1, vcc
	global_store_short_d16_hi v[0:1], v4, off offset:1024
	s_barrier

.LBB0_85:
	s_or_b64 exec, exec, s[2:3]
	v_ashrrev_i32_e32 v5, 10, v32
	v_bfe_u32 v14, v32, 6, 4
	v_mad_i32_i24 v0, v5, 24, v4
	v_lshl_or_b32 v0, v0, 4, v14
	v_ashrrev_i32_e32 v1, 31, v0
	v_lshlrev_b64 v[6:7], 8, v[0:1]
	v_lshlrev_b64 v[0:1], 2, v[192:193]
	v_or_b32_e32 v7, v7, v1
	v_or_b32_e32 v6, v6, v0
	v_lshl_add_u64 v[8:9], s[64:65], 0, v[6:7]
	v_lshl_add_u64 v[6:7], s[66:67], 0, v[6:7]
	s_waitcnt lgkmcnt(0)
	s_barrier
	global_load_dword v23, v[6:7], off
	global_load_dword v24, v[8:9], off
	v_add_u32_e32 v15, 0x100, v32
	v_ashrrev_i32_e32 v17, 10, v15
	v_bfe_u32 v18, v15, 6, 4
	v_mad_i32_i24 v19, v17, 24, v4
	v_lshl_or_b32 v18, v19, 4, v18
	v_ashrrev_i32_e32 v19, 31, v18
	v_lshlrev_b64 v[18:19], 8, v[18:19]
	v_or_b32_e32 v19, v19, v1
	v_or_b32_e32 v18, v18, v0
	v_lshl_add_u64 v[18:19], s[66:67], 0, v[18:19]
	global_load_dword v25, v[18:19], off
	v_add_u32_e32 v15, 0x100, v32
	v_ashrrev_i32_e32 v17, 10, v15
	v_bfe_u32 v18, v15, 6, 4
	v_mad_i32_i24 v19, v17, 24, v4
	v_lshl_or_b32 v18, v19, 4, v18
	v_ashrrev_i32_e32 v19, 31, v18
	v_lshlrev_b64 v[18:19], 8, v[18:19]
	v_or_b32_e32 v19, v19, v1
	v_or_b32_e32 v18, v18, v0
	v_lshl_add_u64 v[20:21], s[64:65], 0, v[18:19]
	global_load_dword v26, v[20:21], off
	v_add_u32_e32 v15, 0x200, v32
	v_ashrrev_i32_e32 v17, 10, v15
	v_bfe_u32 v18, v15, 6, 4
	v_mad_i32_i24 v19, v17, 24, v4
	v_lshl_or_b32 v18, v19, 4, v18
	v_ashrrev_i32_e32 v19, 31, v18
	v_lshlrev_b64 v[18:19], 8, v[18:19]
	v_or_b32_e32 v19, v19, v1
	v_or_b32_e32 v18, v18, v0
	v_lshl_add_u64 v[18:19], s[66:67], 0, v[18:19]
	global_load_dword v27, v[18:19], off
	v_add_u32_e32 v15, 0x200, v32
	v_ashrrev_i32_e32 v17, 10, v15
	v_bfe_u32 v18, v15, 6, 4
	v_mad_i32_i24 v19, v17, 24, v4
	v_lshl_or_b32 v18, v19, 4, v18
	v_ashrrev_i32_e32 v19, 31, v18
	v_lshlrev_b64 v[18:19], 8, v[18:19]
	v_or_b32_e32 v19, v19, v1
	v_or_b32_e32 v18, v18, v0
	v_lshl_add_u64 v[20:21], s[64:65], 0, v[18:19]
	global_load_dword v28, v[20:21], off
	v_add_u32_e32 v15, 0x300, v32
	v_ashrrev_i32_e32 v17, 10, v15
	v_bfe_u32 v18, v15, 6, 4
	v_mad_i32_i24 v19, v17, 24, v4
	v_lshl_or_b32 v18, v19, 4, v18
	v_ashrrev_i32_e32 v19, 31, v18
	v_lshlrev_b64 v[18:19], 8, v[18:19]
	v_or_b32_e32 v19, v19, v1
	v_or_b32_e32 v18, v18, v0
	v_lshl_add_u64 v[18:19], s[66:67], 0, v[18:19]
	global_load_dword v29, v[18:19], off
	v_add_u32_e32 v15, 0x300, v32
	v_ashrrev_i32_e32 v17, 10, v15
	v_bfe_u32 v18, v15, 6, 4
	v_mad_i32_i24 v19, v17, 24, v4
	v_lshl_or_b32 v18, v19, 4, v18
	v_ashrrev_i32_e32 v19, 31, v18
	v_lshlrev_b64 v[18:19], 8, v[18:19]
	v_or_b32_e32 v19, v19, v1
	v_or_b32_e32 v18, v18, v0
	v_lshl_add_u64 v[20:21], s[64:65], 0, v[18:19]
	global_load_dword v30, v[20:21], off
	v_add_u32_e32 v15, 0x400, v32
	v_ashrrev_i32_e32 v17, 10, v15
	v_mad_i32_i24 v18, v17, 24, v4
	v_lshl_or_b32 v18, v18, 4, v14
	v_ashrrev_i32_e32 v19, 31, v18
	v_lshlrev_b64 v[18:19], 8, v[18:19]
	v_or_b32_e32 v19, v19, v1
	v_or_b32_e32 v18, v18, v0
	v_lshl_add_u64 v[18:19], s[66:67], 0, v[18:19]
	global_load_dword v31, v[18:19], off
	v_add_u32_e32 v15, 0x400, v32
	v_ashrrev_i32_e32 v17, 10, v15
	v_mad_i32_i24 v18, v17, 24, v4
	v_lshl_or_b32 v18, v18, 4, v14
	v_ashrrev_i32_e32 v19, 31, v18
	v_lshlrev_b64 v[18:19], 8, v[18:19]
	v_or_b32_e32 v19, v19, v1
	v_or_b32_e32 v18, v18, v0
	v_lshl_add_u64 v[20:21], s[64:65], 0, v[18:19]
	global_load_dword v33, v[20:21], off
	v_add_u32_e32 v15, 0x500, v32
	v_ashrrev_i32_e32 v17, 10, v15
	v_bfe_u32 v18, v15, 6, 4
	v_mad_i32_i24 v19, v17, 24, v4
	v_lshl_or_b32 v18, v19, 4, v18
	v_ashrrev_i32_e32 v19, 31, v18
	v_lshlrev_b64 v[18:19], 8, v[18:19]
	v_or_b32_e32 v19, v19, v1
	v_or_b32_e32 v18, v18, v0
	v_lshl_add_u64 v[18:19], s[66:67], 0, v[18:19]
	global_load_dword v34, v[18:19], off
	v_add_u32_e32 v15, 0x500, v32
	v_ashrrev_i32_e32 v17, 10, v15
	v_bfe_u32 v18, v15, 6, 4
	v_mad_i32_i24 v19, v17, 24, v4
	v_lshl_or_b32 v18, v19, 4, v18
	v_ashrrev_i32_e32 v19, 31, v18
	v_lshlrev_b64 v[18:19], 8, v[18:19]
	v_or_b32_e32 v19, v19, v1
	v_or_b32_e32 v18, v18, v0
	v_lshl_add_u64 v[20:21], s[64:65], 0, v[18:19]
	global_load_dword v35, v[20:21], off
	v_add_u32_e32 v15, 0x600, v32
	v_ashrrev_i32_e32 v17, 10, v15
	v_bfe_u32 v18, v15, 6, 4
	v_mad_i32_i24 v19, v17, 24, v4
	v_lshl_or_b32 v18, v19, 4, v18
	v_ashrrev_i32_e32 v19, 31, v18
	v_lshlrev_b64 v[18:19], 8, v[18:19]
	v_or_b32_e32 v19, v19, v1
	v_or_b32_e32 v18, v18, v0
	v_lshl_add_u64 v[18:19], s[66:67], 0, v[18:19]
	global_load_dword v36, v[18:19], off
	v_add_u32_e32 v15, 0x600, v32
	v_ashrrev_i32_e32 v17, 10, v15
	v_bfe_u32 v18, v15, 6, 4
	v_mad_i32_i24 v19, v17, 24, v4
	v_lshl_or_b32 v18, v19, 4, v18
	v_ashrrev_i32_e32 v19, 31, v18
	v_lshlrev_b64 v[18:19], 8, v[18:19]
	v_or_b32_e32 v19, v19, v1
	v_or_b32_e32 v18, v18, v0
	v_lshl_add_u64 v[20:21], s[64:65], 0, v[18:19]
	global_load_dword v37, v[20:21], off
	v_add_u32_e32 v19, 0x700, v32
	v_ashrrev_i32_e32 v22, 10, v19
	v_bfe_u32 v21, v19, 6, 4
	v_mad_i32_i24 v20, v22, 24, v4
	v_lshl_or_b32 v20, v20, 4, v21
	v_ashrrev_i32_e32 v21, 31, v20
	v_lshlrev_b64 v[20:21], 8, v[20:21]
	v_or_b32_e32 v17, v21, v1
	v_or_b32_e32 v16, v20, v0
	v_lshl_add_u64 v[16:17], s[66:67], 0, v[16:17]
	global_load_dword v38, v[16:17], off
	v_add_u32_e32 v19, 0x700, v32
	v_ashrrev_i32_e32 v22, 10, v19
	v_bfe_u32 v21, v19, 6, 4
	v_mad_i32_i24 v20, v22, 24, v4
	v_lshl_or_b32 v20, v20, 4, v21
	v_ashrrev_i32_e32 v21, 31, v20
	v_lshlrev_b64 v[20:21], 8, v[20:21]
	v_or_b32_e32 v17, v21, v1
	v_or_b32_e32 v16, v20, v0
	v_lshl_add_u64 v[20:21], s[64:65], 0, v[16:17]
	global_load_dword v39, v[20:21], off
	s_waitcnt vmcnt(0)
	v_mov_b32_e32 v6, v23
	v_lshlrev_b32_e32 v2, 3, v192
	v_mov_b32_e32 v8, v24
	v_lshl_add_u32 v5, v5, 9, v2
	ds_read_b64 v[10:11], v5
	s_cmp_lt_u32 s5, 31
	s_waitcnt lgkmcnt(0)
	v_pk_mul_f32 v[6:7], v[6:7], v[10:11] op_sel:[0,1] op_sel_hi:[0,0]
	v_pk_fma_f32 v[12:13], v[8:9], v[10:11], v[6:7] neg_lo:[0,0,1] neg_hi:[0,0,1]
	v_pk_fma_f32 v[6:7], v[8:9], v[10:11], v[6:7] op_sel_hi:[0,1,1]
	v_mov_b32_e32 v13, v7
	ds_write_b64 v3, v[12:13] offset:1024
	v_add_u32_e32 v3, 0x100, v32
	v_ashrrev_i32_e32 v5, 10, v3
	v_bfe_u32 v6, v3, 6, 4
	v_mad_i32_i24 v7, v5, 24, v4
	v_lshl_or_b32 v6, v7, 4, v6
	v_ashrrev_i32_e32 v7, 31, v6
	v_lshlrev_b64 v[6:7], 8, v[6:7]
	v_or_b32_e32 v7, v7, v1
	v_or_b32_e32 v6, v6, v0
	v_lshl_add_u64 v[8:9], s[64:65], 0, v[6:7]
	v_lshl_add_u64 v[6:7], s[66:67], 0, v[6:7]
	v_mov_b32_e32 v6, v25
	v_lshl_add_u32 v5, v5, 9, v2
	v_mov_b32_e32 v8, v26
	ds_read_b64 v[10:11], v5
	v_lshlrev_b32_e32 v3, 3, v3
	s_waitcnt lgkmcnt(0)
	v_pk_mul_f32 v[6:7], v[6:7], v[10:11] op_sel:[0,1] op_sel_hi:[0,0]
	v_pk_fma_f32 v[12:13], v[8:9], v[10:11], v[6:7] neg_lo:[0,0,1] neg_hi:[0,0,1]
	v_pk_fma_f32 v[6:7], v[8:9], v[10:11], v[6:7] op_sel_hi:[0,1,1]
	v_mov_b32_e32 v13, v7
	ds_write_b64 v3, v[12:13] offset:1024
	v_add_u32_e32 v3, 0x200, v32
	v_ashrrev_i32_e32 v5, 10, v3
	v_bfe_u32 v6, v3, 6, 4
	v_mad_i32_i24 v7, v5, 24, v4
	v_lshl_or_b32 v6, v7, 4, v6
	v_ashrrev_i32_e32 v7, 31, v6
	v_lshlrev_b64 v[6:7], 8, v[6:7]
	v_or_b32_e32 v7, v7, v1
	v_or_b32_e32 v6, v6, v0
	v_lshl_add_u64 v[8:9], s[64:65], 0, v[6:7]
	v_lshl_add_u64 v[6:7], s[66:67], 0, v[6:7]
	v_mov_b32_e32 v6, v27
	v_lshl_add_u32 v5, v5, 9, v2
	v_mov_b32_e32 v8, v28
	ds_read_b64 v[10:11], v5
	v_lshlrev_b32_e32 v3, 3, v3
	s_waitcnt lgkmcnt(0)
	v_pk_mul_f32 v[6:7], v[6:7], v[10:11] op_sel:[0,1] op_sel_hi:[0,0]
	v_pk_fma_f32 v[12:13], v[8:9], v[10:11], v[6:7] neg_lo:[0,0,1] neg_hi:[0,0,1]
	v_pk_fma_f32 v[6:7], v[8:9], v[10:11], v[6:7] op_sel_hi:[0,1,1]
	v_mov_b32_e32 v13, v7
	ds_write_b64 v3, v[12:13] offset:1024
	v_add_u32_e32 v3, 0x300, v32
	v_ashrrev_i32_e32 v5, 10, v3
	v_bfe_u32 v6, v3, 6, 4
	v_mad_i32_i24 v7, v5, 24, v4
	v_lshl_or_b32 v6, v7, 4, v6
	v_ashrrev_i32_e32 v7, 31, v6
	v_lshlrev_b64 v[6:7], 8, v[6:7]
	v_or_b32_e32 v7, v7, v1
	v_or_b32_e32 v6, v6, v0
	v_lshl_add_u64 v[8:9], s[64:65], 0, v[6:7]
	v_lshl_add_u64 v[6:7], s[66:67], 0, v[6:7]
	v_mov_b32_e32 v6, v29
	v_lshl_add_u32 v5, v5, 9, v2
	v_mov_b32_e32 v8, v30
	ds_read_b64 v[10:11], v5
	v_lshlrev_b32_e32 v3, 3, v3
	s_waitcnt lgkmcnt(0)
	v_pk_mul_f32 v[6:7], v[6:7], v[10:11] op_sel:[0,1] op_sel_hi:[0,0]
	v_pk_fma_f32 v[12:13], v[8:9], v[10:11], v[6:7] neg_lo:[0,0,1] neg_hi:[0,0,1]
	v_pk_fma_f32 v[6:7], v[8:9], v[10:11], v[6:7] op_sel_hi:[0,1,1]
	v_mov_b32_e32 v13, v7
	ds_write_b64 v3, v[12:13] offset:1024
	v_add_u32_e32 v3, 0x400, v32
	v_ashrrev_i32_e32 v5, 10, v3
	v_mad_i32_i24 v6, v5, 24, v4
	v_lshl_or_b32 v6, v6, 4, v14
	v_ashrrev_i32_e32 v7, 31, v6
	v_lshlrev_b64 v[6:7], 8, v[6:7]
	v_or_b32_e32 v7, v7, v1
	v_or_b32_e32 v6, v6, v0
	v_lshl_add_u64 v[8:9], s[64:65], 0, v[6:7]
	v_lshl_add_u64 v[6:7], s[66:67], 0, v[6:7]
	v_mov_b32_e32 v6, v31
	v_lshl_add_u32 v5, v5, 9, v2
	v_mov_b32_e32 v8, v33
	ds_read_b64 v[10:11], v5
	v_lshlrev_b32_e32 v3, 3, v3
	s_waitcnt lgkmcnt(0)
	v_pk_mul_f32 v[6:7], v[6:7], v[10:11] op_sel:[0,1] op_sel_hi:[0,0]
	v_pk_fma_f32 v[12:13], v[8:9], v[10:11], v[6:7] neg_lo:[0,0,1] neg_hi:[0,0,1]
	v_pk_fma_f32 v[6:7], v[8:9], v[10:11], v[6:7] op_sel_hi:[0,1,1]
	v_mov_b32_e32 v13, v7
	ds_write_b64 v3, v[12:13] offset:1024
	v_add_u32_e32 v3, 0x500, v32
	v_ashrrev_i32_e32 v5, 10, v3
	v_bfe_u32 v6, v3, 6, 4
	v_mad_i32_i24 v7, v5, 24, v4
	v_lshl_or_b32 v6, v7, 4, v6
	v_ashrrev_i32_e32 v7, 31, v6
	v_lshlrev_b64 v[6:7], 8, v[6:7]
	v_or_b32_e32 v7, v7, v1
	v_or_b32_e32 v6, v6, v0
	v_lshl_add_u64 v[8:9], s[64:65], 0, v[6:7]
	v_lshl_add_u64 v[6:7], s[66:67], 0, v[6:7]
	v_mov_b32_e32 v6, v34
	v_lshl_add_u32 v5, v5, 9, v2
	v_mov_b32_e32 v8, v35
	ds_read_b64 v[10:11], v5
	v_lshlrev_b32_e32 v3, 3, v3
	s_waitcnt lgkmcnt(0)
	v_pk_mul_f32 v[6:7], v[6:7], v[10:11] op_sel:[0,1] op_sel_hi:[0,0]
	v_pk_fma_f32 v[12:13], v[8:9], v[10:11], v[6:7] neg_lo:[0,0,1] neg_hi:[0,0,1]
	v_pk_fma_f32 v[6:7], v[8:9], v[10:11], v[6:7] op_sel_hi:[0,1,1]
	v_mov_b32_e32 v13, v7
	ds_write_b64 v3, v[12:13] offset:1024
	v_add_u32_e32 v3, 0x600, v32
	v_ashrrev_i32_e32 v5, 10, v3
	v_bfe_u32 v6, v3, 6, 4
	v_mad_i32_i24 v7, v5, 24, v4
	v_lshl_or_b32 v6, v7, 4, v6
	v_ashrrev_i32_e32 v7, 31, v6
	v_lshlrev_b64 v[6:7], 8, v[6:7]
	v_or_b32_e32 v7, v7, v1
	v_or_b32_e32 v6, v6, v0
	v_lshl_add_u64 v[8:9], s[64:65], 0, v[6:7]
	v_lshl_add_u64 v[6:7], s[66:67], 0, v[6:7]
	v_mov_b32_e32 v6, v36
	v_lshl_add_u32 v5, v5, 9, v2
	v_mov_b32_e32 v8, v37
	ds_read_b64 v[10:11], v5
	v_lshlrev_b32_e32 v3, 3, v3
	s_waitcnt lgkmcnt(0)
	v_pk_mul_f32 v[6:7], v[6:7], v[10:11] op_sel:[0,1] op_sel_hi:[0,0]
	v_pk_fma_f32 v[12:13], v[8:9], v[10:11], v[6:7] neg_lo:[0,0,1] neg_hi:[0,0,1]
	v_pk_fma_f32 v[6:7], v[8:9], v[10:11], v[6:7] op_sel_hi:[0,1,1]
	v_mov_b32_e32 v13, v7
	ds_write_b64 v3, v[12:13] offset:1024
	v_add_u32_e32 v3, 0x700, v32
	v_ashrrev_i32_e32 v6, 10, v3
	v_bfe_u32 v5, v3, 6, 4
	v_mad_i32_i24 v4, v6, 24, v4
	v_lshl_or_b32 v4, v4, 4, v5
	v_ashrrev_i32_e32 v5, 31, v4
	v_lshlrev_b64 v[4:5], 8, v[4:5]
	v_or_b32_e32 v1, v5, v1
	v_or_b32_e32 v0, v4, v0
	v_lshl_add_u64 v[4:5], s[64:65], 0, v[0:1]
	v_lshl_add_u64 v[0:1], s[66:67], 0, v[0:1]
	v_mov_b32_e32 v0, v38
	v_lshl_add_u32 v1, v6, 9, v2
	v_mov_b32_e32 v4, v39
	v_lshlrev_b32_e32 v5, 3, v3
	ds_read_b64 v[2:3], v1
	s_waitcnt lgkmcnt(0)
	v_pk_mul_f32 v[0:1], v[0:1], v[2:3] op_sel:[0,1] op_sel_hi:[0,0]
	v_pk_fma_f32 v[6:7], v[4:5], v[2:3], v[0:1] neg_lo:[0,0,1] neg_hi:[0,0,1]
	v_pk_fma_f32 v[0:1], v[4:5], v[2:3], v[0:1] op_sel_hi:[0,1,1]
	v_ashrrev_i32_e32 v0, 4, v32
	v_mov_b32_e32 v7, v1
	v_and_b32_e32 v1, 15, v32
	v_lshlrev_b32_e32 v3, 9, v0
	v_mov_b32_e32 v2, 0
	ds_write_b64 v5, v[6:7] offset:1024
	s_waitcnt lgkmcnt(0)
	s_barrier
	s_cbranch_scc1 .LBB0_88
	v_add_u32_e32 v4, 0x400, v3
	v_lshl_or_b32 v5, v1, 2, v245
	v_mov_b32_e32 v2, 0
	s_mov_b32 s1, 0

.Lrs1_top:
	s_add_i32 s7, s6, 64
	s_min_u32 s8, s7, 0xae0
	s_lshl_b32 s78, s8, 1
	ds_read_b128 v[52:55], v116 offset:0
	ds_read_b128 v[48:51], v116 offset:0x800
	ds_read_b128 v[44:47], v116 offset:0x1000
	ds_read_b128 v[96:99], v114 offset:0
	v_mfma_f32_32x32x16_bf16 a[144:159], v[128:131], v[40:43], a[144:159]
	ds_read_b128 v[92:95], v114 offset:0x800
	v_mfma_f32_32x32x16_bf16 a[160:175], v[128:131], v[36:39], a[160:175]
	ds_read_b128 v[88:91], v114 offset:0x1000
	v_lshl_add_u64 v[60:61], v[100:101], 0, s[78:79]
	global_load_dwordx4 v[64:67], v[60:61], off
	v_mfma_f32_32x32x16_bf16 a[176:191], v[128:131], v[194:197], a[176:191]
	ds_read_b128 v[56:59], v114 offset:0x1800
	v_lshl_add_u64 v[62:63], v[104:105], 0, s[78:79]
	global_load_dwordx4 v[60:63], v[62:63], off
	v_mfma_f32_32x32x16_bf16 a[32:47], v[198:201], v[40:43], a[32:47]
	v_lshl_add_u64 v[68:69], v[106:107], 0, s[78:79]
	global_load_dwordx4 v[72:75], v[68:69], off
	v_mfma_f32_32x32x16_bf16 a[16:31], v[198:201], v[36:39], a[16:31]
	v_lshl_add_u64 v[70:71], v[108:109], 0, s[78:79]
	global_load_dwordx4 v[68:71], v[70:71], off
	v_mfma_f32_32x32x16_bf16 a[0:15], v[198:201], v[194:197], a[0:15]
	v_lshl_add_u64 v[76:77], v[102:103], 0, s[78:79]
	global_load_dwordx4 v[84:87], v[76:77], off
	s_waitcnt lgkmcnt(3)
	v_mfma_f32_32x32x16_bf16 a[48:63], v[96:99], v[52:55], a[48:63]
	ds_read_b128 v[36:39], v117 offset:0
	v_mfma_f32_32x32x16_bf16 a[64:79], v[96:99], v[48:51], a[64:79]
	v_lshl_add_u64 v[78:79], v[110:111], 0, s[78:79]
	global_load_dwordx4 v[76:79], v[78:79], off
	v_mfma_f32_32x32x16_bf16 a[80:95], v[96:99], v[44:47], a[80:95]
	ds_read_b128 v[40:43], v117 offset:0x800
	s_waitcnt lgkmcnt(4)
	v_mfma_f32_32x32x16_bf16 a[96:111], v[92:95], v[52:55], a[96:111]
	v_lshl_add_u64 v[80:81], v[112:113], 0, s[78:79]
	global_load_dwordx4 v[80:83], v[80:81], off
	v_mfma_f32_32x32x16_bf16 a[112:127], v[92:95], v[48:51], a[112:127]
	ds_read_b128 v[120:123], v117 offset:0x1000
	s_min_u32 s6, s6, 0xa80
	s_lshl_b32 s78, s6, 1
	v_mfma_f32_32x32x16_bf16 a[128:143], v[92:95], v[44:47], a[128:143]
	ds_read_b128 v[124:127], v115 offset:0
	s_add_i32 s8, s78, 0xc0
	s_mov_b32 s9, s79
	s_waitcnt lgkmcnt(5)
	v_mfma_f32_32x32x16_bf16 a[144:159], v[88:91], v[52:55], a[144:159]
	ds_read_b128 v[128:131], v115 offset:0x800
	s_add_i32 s5, s5, 2
	s_cmpk_lt_u32 s5, 0x54
	v_mfma_f32_32x32x16_bf16 a[160:175], v[88:91], v[48:51], a[160:175]
	ds_read_b128 v[132:135], v115 offset:0x1000
	s_waitcnt vmcnt(13)
	ds_write_b128 v118, v[4:7] offset:0x8000
	v_mfma_f32_32x32x16_bf16 a[176:191], v[88:91], v[44:47], a[176:191]
	ds_read_b128 v[136:139], v115 offset:0x1800
	s_waitcnt vmcnt(12)
	ds_write_b128 v118, v[8:11] offset:0x9000
	s_waitcnt lgkmcnt(9)
	v_mfma_f32_32x32x16_bf16 a[32:47], v[56:59], v[52:55], a[32:47]
	s_waitcnt vmcnt(11)
	ds_write_b128 v118, v[12:15] offset:0xa000
	v_mfma_f32_32x32x16_bf16 a[16:31], v[56:59], v[48:51], a[16:31]
	s_waitcnt vmcnt(10)
	ds_write_b128 v118, v[16:19] offset:0xb000
	v_mfma_f32_32x32x16_bf16 a[0:15], v[56:59], v[44:47], a[0:15]
	s_waitcnt vmcnt(9)
	ds_write_b128 v118, v[20:23] offset:0xc000
	s_waitcnt lgkmcnt(8)
	v_mfma_f32_32x32x16_bf16 a[48:63], v[124:127], v[36:39], a[48:63]
	s_waitcnt vmcnt(8)
	ds_write_b128 v118, v[24:27] offset:0xd000
	v_mfma_f32_32x32x16_bf16 a[64:79], v[124:127], v[40:43], a[64:79]
	s_waitcnt vmcnt(7)
	ds_write_b128 v118, v[28:31] offset:0xe000
	v_mfma_f32_32x32x16_bf16 a[80:95], v[124:127], v[120:123], a[80:95]
	v_lshl_add_u64 v[4:5], v[100:101], 0, s[78:79]
	v_lshl_add_u64 v[8:9], v[104:105], 0, s[8:9]
	s_waitcnt lgkmcnt(9)
	v_mfma_f32_32x32x16_bf16 a[96:111], v[128:131], v[36:39], a[96:111]
	v_lshl_add_u64 v[12:13], v[106:107], 0, s[8:9]
	v_lshl_add_u64 v[16:17], v[108:109], 0, s[8:9]
	v_mfma_f32_32x32x16_bf16 a[112:127], v[128:131], v[40:43], a[112:127]
	v_lshl_add_u64 v[20:21], v[102:103], 0, s[78:79]
	v_lshl_add_u64 v[24:25], v[110:111], 0, s[8:9]
	v_mfma_f32_32x32x16_bf16 a[128:143], v[128:131], v[120:123], a[128:143]
	v_lshl_add_u64 v[28:29], v[112:113], 0, s[8:9]
	s_waitcnt lgkmcnt(0)
	s_barrier
	ds_read_b128 v[44:47], v116 offset:0x8000
	ds_read_b128 v[48:51], v116 offset:0x8800
	ds_read_b128 v[52:55], v116 offset:0x9000
	ds_read_b128 v[56:59], v114 offset:0x8000
	v_mfma_f32_32x32x16_bf16 a[144:159], v[132:135], v[36:39], a[144:159]
	ds_read_b128 v[88:91], v114 offset:0x8800
	v_mfma_f32_32x32x16_bf16 a[160:175], v[132:135], v[40:43], a[160:175]
	ds_read_b128 v[92:95], v114 offset:0x9000
	global_load_dwordx4 v[4:7], v[4:5], off offset:192
	v_mfma_f32_32x32x16_bf16 a[176:191], v[132:135], v[120:123], a[176:191]
	ds_read_b128 v[96:99], v114 offset:0x9800
	global_load_dwordx4 v[8:11], v[8:9], off
	v_mfma_f32_32x32x16_bf16 a[32:47], v[136:139], v[36:39], a[32:47]
	global_load_dwordx4 v[12:15], v[12:13], off
	v_mfma_f32_32x32x16_bf16 a[16:31], v[136:139], v[40:43], a[16:31]
	global_load_dwordx4 v[16:19], v[16:17], off
	v_mfma_f32_32x32x16_bf16 a[0:15], v[136:139], v[120:123], a[0:15]
	global_load_dwordx4 v[20:23], v[20:21], off offset:192
	s_waitcnt lgkmcnt(3)
	v_mfma_f32_32x32x16_bf16 a[48:63], v[56:59], v[44:47], a[48:63]
	ds_read_b128 v[40:43], v117 offset:0x8000
	v_mfma_f32_32x32x16_bf16 a[64:79], v[56:59], v[48:51], a[64:79]
	global_load_dwordx4 v[24:27], v[24:25], off
	v_mfma_f32_32x32x16_bf16 a[80:95], v[56:59], v[52:55], a[80:95]
	ds_read_b128 v[36:39], v117 offset:0x8800
	s_waitcnt lgkmcnt(4)
	v_mfma_f32_32x32x16_bf16 a[96:111], v[88:91], v[44:47], a[96:111]
	global_load_dwordx4 v[28:31], v[28:29], off
	v_mfma_f32_32x32x16_bf16 a[112:127], v[88:91], v[48:51], a[112:127]
	ds_read_b128 v[194:197], v117 offset:0x9000
	v_mfma_f32_32x32x16_bf16 a[128:143], v[88:91], v[52:55], a[128:143]
	ds_read_b128 v[120:123], v115 offset:0x8000
	s_waitcnt lgkmcnt(5)
	v_mfma_f32_32x32x16_bf16 a[144:159], v[92:95], v[44:47], a[144:159]
	ds_read_b128 v[124:127], v115 offset:0x8800
	v_mfma_f32_32x32x16_bf16 a[160:175], v[92:95], v[48:51], a[160:175]
	ds_read_b128 v[128:131], v115 offset:0x9000
	v_mfma_f32_32x32x16_bf16 a[176:191], v[92:95], v[52:55], a[176:191]
	ds_read_b128 v[198:201], v115 offset:0x9800
	s_waitcnt lgkmcnt(7)
	v_mfma_f32_32x32x16_bf16 a[32:47], v[96:99], v[44:47], a[32:47]
	s_waitcnt vmcnt(13)
	ds_write_b128 v118, v[64:67] offset:0
	v_mfma_f32_32x32x16_bf16 a[16:31], v[96:99], v[48:51], a[16:31]
	s_waitcnt vmcnt(12)
	ds_write_b128 v118, v[60:63] offset:0x1000
	v_mfma_f32_32x32x16_bf16 a[0:15], v[96:99], v[52:55], a[0:15]
	s_waitcnt vmcnt(11)
	ds_write_b128 v118, v[72:75] offset:0x2000
	s_waitcnt lgkmcnt(6)
	v_mfma_f32_32x32x16_bf16 a[48:63], v[120:123], v[40:43], a[48:63]
	s_waitcnt vmcnt(10)
	ds_write_b128 v118, v[68:71] offset:0x3000
	v_mfma_f32_32x32x16_bf16 a[64:79], v[120:123], v[36:39], a[64:79]
	s_waitcnt vmcnt(9)
	ds_write_b128 v118, v[84:87] offset:0x4000
	v_mfma_f32_32x32x16_bf16 a[80:95], v[120:123], v[194:197], a[80:95]
	s_waitcnt vmcnt(8)
	ds_write_b128 v118, v[76:79] offset:0x5000
	s_waitcnt lgkmcnt(8)
	v_mfma_f32_32x32x16_bf16 a[96:111], v[124:127], v[40:43], a[96:111]
	s_waitcnt vmcnt(7)
	ds_write_b128 v118, v[80:83] offset:0x6000
	v_mfma_f32_32x32x16_bf16 a[112:127], v[124:127], v[36:39], a[112:127]
	v_mfma_f32_32x32x16_bf16 a[128:143], v[124:127], v[194:197], a[128:143]
	s_waitcnt lgkmcnt(0)
	s_barrier
	s_cbranch_scc0 .Lrs1_last
	s_mov_b32 s6, s7
	s_branch .Lrs1_top
.Lrs1_last:
	s_mov_b32 s6, s7
	s_add_i32 s7, s6, 64
	s_min_u32 s8, s7, 0xae0
	s_lshl_b32 s78, s8, 1
	ds_read_b128 v[52:55], v116 offset:0
	ds_read_b128 v[48:51], v116 offset:0x800
	ds_read_b128 v[44:47], v116 offset:0x1000
	ds_read_b128 v[96:99], v114 offset:0
	v_mfma_f32_32x32x16_bf16 a[144:159], v[128:131], v[40:43], a[144:159]
	ds_read_b128 v[92:95], v114 offset:0x800
	v_mfma_f32_32x32x16_bf16 a[160:175], v[128:131], v[36:39], a[160:175]
	ds_read_b128 v[88:91], v114 offset:0x1000
	v_mfma_f32_32x32x16_bf16 a[176:191], v[128:131], v[194:197], a[176:191]
	ds_read_b128 v[56:59], v114 offset:0x1800
	v_mfma_f32_32x32x16_bf16 a[32:47], v[198:201], v[40:43], a[32:47]
	v_mfma_f32_32x32x16_bf16 a[16:31], v[198:201], v[36:39], a[16:31]
	v_mfma_f32_32x32x16_bf16 a[0:15], v[198:201], v[194:197], a[0:15]
	s_waitcnt lgkmcnt(3)
	v_mfma_f32_32x32x16_bf16 a[48:63], v[96:99], v[52:55], a[48:63]
	ds_read_b128 v[36:39], v117 offset:0
	v_mfma_f32_32x32x16_bf16 a[64:79], v[96:99], v[48:51], a[64:79]
	v_mfma_f32_32x32x16_bf16 a[80:95], v[96:99], v[44:47], a[80:95]
	ds_read_b128 v[40:43], v117 offset:0x800
	s_waitcnt lgkmcnt(4)
	v_mfma_f32_32x32x16_bf16 a[96:111], v[92:95], v[52:55], a[96:111]
	v_mfma_f32_32x32x16_bf16 a[112:127], v[92:95], v[48:51], a[112:127]
	ds_read_b128 v[120:123], v117 offset:0x1000
	s_min_u32 s6, s6, 0xa80
	s_lshl_b32 s78, s6, 1
	v_mfma_f32_32x32x16_bf16 a[128:143], v[92:95], v[44:47], a[128:143]
	ds_read_b128 v[124:127], v115 offset:0
	s_add_i32 s8, s78, 0xc0
	s_mov_b32 s9, s79
	s_waitcnt lgkmcnt(5)
	v_mfma_f32_32x32x16_bf16 a[144:159], v[88:91], v[52:55], a[144:159]
	ds_read_b128 v[128:131], v115 offset:0x800
	s_add_i32 s5, s5, 2
	s_cmpk_lt_u32 s5, 0x56
	v_mfma_f32_32x32x16_bf16 a[160:175], v[88:91], v[48:51], a[160:175]
	ds_read_b128 v[132:135], v115 offset:0x1000
	s_waitcnt vmcnt(6)
	ds_write_b128 v118, v[4:7] offset:0x8000
	v_mfma_f32_32x32x16_bf16 a[176:191], v[88:91], v[44:47], a[176:191]
	ds_read_b128 v[136:139], v115 offset:0x1800
	s_waitcnt vmcnt(5)
	ds_write_b128 v118, v[8:11] offset:0x9000
	s_waitcnt lgkmcnt(9)
	v_mfma_f32_32x32x16_bf16 a[32:47], v[56:59], v[52:55], a[32:47]
	s_waitcnt vmcnt(4)
	ds_write_b128 v118, v[12:15] offset:0xa000
	v_mfma_f32_32x32x16_bf16 a[16:31], v[56:59], v[48:51], a[16:31]
	s_waitcnt vmcnt(3)
	ds_write_b128 v118, v[16:19] offset:0xb000
	v_mfma_f32_32x32x16_bf16 a[0:15], v[56:59], v[44:47], a[0:15]
	s_waitcnt vmcnt(2)
	ds_write_b128 v118, v[20:23] offset:0xc000
	s_waitcnt lgkmcnt(8)
	v_mfma_f32_32x32x16_bf16 a[48:63], v[124:127], v[36:39], a[48:63]
	s_waitcnt vmcnt(1)
	ds_write_b128 v118, v[24:27] offset:0xd000
	v_mfma_f32_32x32x16_bf16 a[64:79], v[124:127], v[40:43], a[64:79]
	s_waitcnt vmcnt(0)
	ds_write_b128 v118, v[28:31] offset:0xe000
	v_mfma_f32_32x32x16_bf16 a[80:95], v[124:127], v[120:123], a[80:95]
	s_waitcnt lgkmcnt(9)
	v_mfma_f32_32x32x16_bf16 a[96:111], v[128:131], v[36:39], a[96:111]
	v_mfma_f32_32x32x16_bf16 a[112:127], v[128:131], v[40:43], a[112:127]
	v_mfma_f32_32x32x16_bf16 a[128:143], v[128:131], v[120:123], a[128:143]
	s_waitcnt lgkmcnt(0)
	s_barrier
	ds_read_b128 v[44:47], v116 offset:0x8000
	ds_read_b128 v[48:51], v116 offset:0x8800
	ds_read_b128 v[52:55], v116 offset:0x9000
	ds_read_b128 v[56:59], v114 offset:0x8000
	v_mfma_f32_32x32x16_bf16 a[144:159], v[132:135], v[36:39], a[144:159]
	ds_read_b128 v[88:91], v114 offset:0x8800
	v_mfma_f32_32x32x16_bf16 a[160:175], v[132:135], v[40:43], a[160:175]
	ds_read_b128 v[92:95], v114 offset:0x9000
	v_mfma_f32_32x32x16_bf16 a[176:191], v[132:135], v[120:123], a[176:191]
	ds_read_b128 v[96:99], v114 offset:0x9800
	v_mfma_f32_32x32x16_bf16 a[32:47], v[136:139], v[36:39], a[32:47]
	v_mfma_f32_32x32x16_bf16 a[16:31], v[136:139], v[40:43], a[16:31]
	v_mfma_f32_32x32x16_bf16 a[0:15], v[136:139], v[120:123], a[0:15]
	s_waitcnt lgkmcnt(3)
	v_mfma_f32_32x32x16_bf16 a[48:63], v[56:59], v[44:47], a[48:63]
	ds_read_b128 v[40:43], v117 offset:0x8000
	v_mfma_f32_32x32x16_bf16 a[64:79], v[56:59], v[48:51], a[64:79]
	v_mfma_f32_32x32x16_bf16 a[80:95], v[56:59], v[52:55], a[80:95]
	ds_read_b128 v[36:39], v117 offset:0x8800
	s_waitcnt lgkmcnt(4)
	v_mfma_f32_32x32x16_bf16 a[96:111], v[88:91], v[44:47], a[96:111]
	v_mfma_f32_32x32x16_bf16 a[112:127], v[88:91], v[48:51], a[112:127]
	ds_read_b128 v[194:197], v117 offset:0x9000
	v_mfma_f32_32x32x16_bf16 a[128:143], v[88:91], v[52:55], a[128:143]
	ds_read_b128 v[120:123], v115 offset:0x8000
	s_waitcnt lgkmcnt(5)
	v_mfma_f32_32x32x16_bf16 a[144:159], v[92:95], v[44:47], a[144:159]
	ds_read_b128 v[124:127], v115 offset:0x8800
	v_mfma_f32_32x32x16_bf16 a[160:175], v[92:95], v[48:51], a[160:175]
	ds_read_b128 v[128:131], v115 offset:0x9000
	v_mfma_f32_32x32x16_bf16 a[176:191], v[92:95], v[52:55], a[176:191]
	ds_read_b128 v[198:201], v115 offset:0x9800
	s_waitcnt lgkmcnt(7)
	v_mfma_f32_32x32x16_bf16 a[32:47], v[96:99], v[44:47], a[32:47]
	v_mfma_f32_32x32x16_bf16 a[16:31], v[96:99], v[48:51], a[16:31]
	v_mfma_f32_32x32x16_bf16 a[0:15], v[96:99], v[52:55], a[0:15]
	s_waitcnt lgkmcnt(3)
	v_mfma_f32_32x32x16_bf16 a[48:63], v[120:123], v[40:43], a[48:63]
	v_mfma_f32_32x32x16_bf16 a[64:79], v[120:123], v[36:39], a[64:79]
	v_mfma_f32_32x32x16_bf16 a[80:95], v[120:123], v[194:197], a[80:95]
	s_waitcnt lgkmcnt(2)
	v_mfma_f32_32x32x16_bf16 a[96:111], v[124:127], v[40:43], a[96:111]
	v_mfma_f32_32x32x16_bf16 a[112:127], v[124:127], v[36:39], a[112:127]
	v_mfma_f32_32x32x16_bf16 a[128:143], v[124:127], v[194:197], a[128:143]
	s_waitcnt lgkmcnt(0)
	s_barrier
	v_mfma_f32_32x32x16_bf16 a[144:159], v[128:131], v[40:43], a[144:159]
	v_mfma_f32_32x32x16_bf16 a[160:175], v[128:131], v[36:39], a[160:175]
	v_mfma_f32_32x32x16_bf16 a[176:191], v[128:131], v[194:197], a[176:191]
	s_nop 7
	s_nop 3
	s_branch .LBB0_120

.Lrs2_top:
	s_add_i32 s5, s4, 64
	s_min_u32 s6, s5, 0xae0
	s_lshl_b32 s78, s6, 1
	ds_read_b128 v[48:51], v82 offset:0
	ds_read_b128 v[44:47], v82 offset:0x800
	ds_read_b128 v[64:67], v80 offset:0
	v_mfma_f32_32x32x16_bf16 a[96:111], v[94:97], v[40:43], a[96:111]
	ds_read_b128 v[60:63], v80 offset:0x800
	v_mfma_f32_32x32x16_bf16 a[112:127], v[94:97], v[128:131], a[112:127]
	ds_read_b128 v[56:59], v80 offset:0x1000
	v_lshl_add_u64 v[106:107], v[68:69], 0, s[78:79]
	global_load_dwordx4 v[106:109], v[106:107], off
	v_mfma_f32_32x32x16_bf16 a[16:31], v[132:135], v[40:43], a[16:31]
	ds_read_b128 v[52:55], v80 offset:0x1800
	v_lshl_add_u64 v[110:111], v[72:73], 0, s[78:79]
	global_load_dwordx4 v[110:113], v[110:111], off
	v_mfma_f32_32x32x16_bf16 a[0:15], v[132:135], v[128:131], a[0:15]
	v_lshl_add_u64 v[114:115], v[74:75], 0, s[78:79]
	global_load_dwordx4 v[114:117], v[114:115], off
	s_waitcnt lgkmcnt(3)
	v_mfma_f32_32x32x16_bf16 a[32:47], v[64:67], v[48:51], a[32:47]
	ds_read_b128 v[40:43], v83 offset:0
	v_mfma_f32_32x32x16_bf16 a[48:63], v[64:67], v[44:47], a[48:63]
	v_lshl_add_u64 v[118:119], v[76:77], 0, s[78:79]
	global_load_dwordx4 v[118:121], v[118:119], off
	s_waitcnt lgkmcnt(3)
	v_mfma_f32_32x32x16_bf16 a[64:79], v[60:63], v[48:51], a[64:79]
	ds_read_b128 v[86:89], v83 offset:0x800
	v_mfma_f32_32x32x16_bf16 a[80:95], v[60:63], v[44:47], a[80:95]
	v_lshl_add_u64 v[122:123], v[70:71], 0, s[78:79]
	global_load_dwordx4 v[122:125], v[122:123], off
	s_waitcnt lgkmcnt(3)
	v_mfma_f32_32x32x16_bf16 a[96:111], v[56:59], v[48:51], a[96:111]
	ds_read_b128 v[90:93], v81 offset:0
	v_mfma_f32_32x32x16_bf16 a[112:127], v[56:59], v[44:47], a[112:127]
	v_lshl_add_u64 v[126:127], v[78:79], 0, s[78:79]
	global_load_dwordx4 v[140:143], v[126:127], off
	s_waitcnt vmcnt(11)
	ds_write_b128 v84, v[4:7] offset:0x8000
	s_waitcnt lgkmcnt(4)
	v_mfma_f32_32x32x16_bf16 a[16:31], v[52:55], v[48:51], a[16:31]
	ds_read_b128 v[94:97], v81 offset:0x800
	s_min_u32 s4, s4, 0xa80
	s_lshl_b32 s78, s4, 1
	s_waitcnt vmcnt(10)
	ds_write_b128 v84, v[8:11] offset:0x9000
	v_mfma_f32_32x32x16_bf16 a[0:15], v[52:55], v[44:47], a[0:15]
	ds_read_b128 v[98:101], v81 offset:0x1000
	s_add_i32 s6, s78, 0xc0
	s_mov_b32 s7, s79
	s_waitcnt vmcnt(9)
	ds_write_b128 v84, v[12:15] offset:0xa000
	s_waitcnt lgkmcnt(5)
	v_mfma_f32_32x32x16_bf16 a[32:47], v[90:93], v[40:43], a[32:47]
	ds_read_b128 v[102:105], v81 offset:0x1800
	s_add_i32 s3, s3, 2
	s_cmpk_lt_u32 s3, 0x54
	s_waitcnt vmcnt(8)
	ds_write_b128 v84, v[16:19] offset:0xb000
	v_mfma_f32_32x32x16_bf16 a[48:63], v[90:93], v[86:89], a[48:63]
	s_waitcnt vmcnt(7)
	ds_write_b128 v84, v[20:23] offset:0xc000
	s_waitcnt lgkmcnt(6)
	v_mfma_f32_32x32x16_bf16 a[64:79], v[94:97], v[40:43], a[64:79]
	s_waitcnt vmcnt(6)
	ds_write_b128 v84, v[24:27] offset:0xd000
	v_mfma_f32_32x32x16_bf16 a[80:95], v[94:97], v[86:89], a[80:95]
	v_lshl_add_u64 v[4:5], v[68:69], 0, s[78:79]
	v_lshl_add_u64 v[8:9], v[72:73], 0, s[6:7]
	v_lshl_add_u64 v[12:13], v[74:75], 0, s[6:7]
	v_lshl_add_u64 v[16:17], v[76:77], 0, s[6:7]
	v_lshl_add_u64 v[20:21], v[70:71], 0, s[78:79]
	v_lshl_add_u64 v[24:25], v[78:79], 0, s[6:7]
	s_waitcnt lgkmcnt(0)
	s_barrier
	ds_read_b128 v[44:47], v82 offset:0x8000
	ds_read_b128 v[48:51], v82 offset:0x8800
	ds_read_b128 v[52:55], v80 offset:0x8000
	v_mfma_f32_32x32x16_bf16 a[96:111], v[98:101], v[40:43], a[96:111]
	ds_read_b128 v[56:59], v80 offset:0x8800
	v_mfma_f32_32x32x16_bf16 a[112:127], v[98:101], v[86:89], a[112:127]
	ds_read_b128 v[60:63], v80 offset:0x9000
	global_load_dwordx4 v[4:7], v[4:5], off offset:192
	v_mfma_f32_32x32x16_bf16 a[16:31], v[102:105], v[40:43], a[16:31]
	ds_read_b128 v[64:67], v80 offset:0x9800
	global_load_dwordx4 v[8:11], v[8:9], off
	v_mfma_f32_32x32x16_bf16 a[0:15], v[102:105], v[86:89], a[0:15]
	global_load_dwordx4 v[12:15], v[12:13], off
	s_waitcnt lgkmcnt(3)
	v_mfma_f32_32x32x16_bf16 a[32:47], v[52:55], v[44:47], a[32:47]
	ds_read_b128 v[40:43], v83 offset:0x8000
	v_mfma_f32_32x32x16_bf16 a[48:63], v[52:55], v[48:51], a[48:63]
	global_load_dwordx4 v[16:19], v[16:17], off
	s_waitcnt lgkmcnt(3)
	v_mfma_f32_32x32x16_bf16 a[64:79], v[56:59], v[44:47], a[64:79]
	ds_read_b128 v[128:131], v83 offset:0x8800
	v_mfma_f32_32x32x16_bf16 a[80:95], v[56:59], v[48:51], a[80:95]
	global_load_dwordx4 v[20:23], v[20:21], off offset:192
	s_waitcnt lgkmcnt(3)
	v_mfma_f32_32x32x16_bf16 a[96:111], v[60:63], v[44:47], a[96:111]
	ds_read_b128 v[86:89], v81 offset:0x8000
	v_mfma_f32_32x32x16_bf16 a[112:127], v[60:63], v[48:51], a[112:127]
	global_load_dwordx4 v[24:27], v[24:25], off
	s_waitcnt vmcnt(11)
	ds_write_b128 v84, v[106:109] offset:0
	s_waitcnt lgkmcnt(4)
	v_mfma_f32_32x32x16_bf16 a[16:31], v[64:67], v[44:47], a[16:31]
	ds_read_b128 v[90:93], v81 offset:0x8800
	s_waitcnt vmcnt(10)
	ds_write_b128 v84, v[110:113] offset:0x1000
	v_mfma_f32_32x32x16_bf16 a[0:15], v[64:67], v[48:51], a[0:15]
	ds_read_b128 v[94:97], v81 offset:0x9000
	s_waitcnt vmcnt(9)
	ds_write_b128 v84, v[114:117] offset:0x2000
	s_waitcnt lgkmcnt(5)
	v_mfma_f32_32x32x16_bf16 a[32:47], v[86:89], v[40:43], a[32:47]
	ds_read_b128 v[132:135], v81 offset:0x9800
	s_waitcnt vmcnt(8)
	ds_write_b128 v84, v[118:121] offset:0x3000
	v_mfma_f32_32x32x16_bf16 a[48:63], v[86:89], v[128:131], a[48:63]
	s_waitcnt vmcnt(7)
	ds_write_b128 v84, v[122:125] offset:0x4000
	s_waitcnt lgkmcnt(6)
	v_mfma_f32_32x32x16_bf16 a[64:79], v[90:93], v[40:43], a[64:79]
	s_waitcnt vmcnt(6)
	ds_write_b128 v84, v[140:143] offset:0x5000
	v_mfma_f32_32x32x16_bf16 a[80:95], v[90:93], v[128:131], a[80:95]
	s_waitcnt lgkmcnt(0)
	s_barrier
	s_cbranch_scc0 .Lrs2_last
	s_mov_b32 s4, s5
	s_branch .Lrs2_top
.Lrs2_last:
	s_mov_b32 s4, s5
	s_add_i32 s5, s4, 64
	s_min_u32 s6, s5, 0xae0
	s_lshl_b32 s78, s6, 1
	ds_read_b128 v[48:51], v82 offset:0
	ds_read_b128 v[44:47], v82 offset:0x800
	ds_read_b128 v[64:67], v80 offset:0
	v_mfma_f32_32x32x16_bf16 a[96:111], v[94:97], v[40:43], a[96:111]
	ds_read_b128 v[60:63], v80 offset:0x800
	v_mfma_f32_32x32x16_bf16 a[112:127], v[94:97], v[128:131], a[112:127]
	ds_read_b128 v[56:59], v80 offset:0x1000
	v_mfma_f32_32x32x16_bf16 a[16:31], v[132:135], v[40:43], a[16:31]
	ds_read_b128 v[52:55], v80 offset:0x1800
	v_mfma_f32_32x32x16_bf16 a[0:15], v[132:135], v[128:131], a[0:15]
	s_waitcnt lgkmcnt(3)
	v_mfma_f32_32x32x16_bf16 a[32:47], v[64:67], v[48:51], a[32:47]
	ds_read_b128 v[40:43], v83 offset:0
	v_mfma_f32_32x32x16_bf16 a[48:63], v[64:67], v[44:47], a[48:63]
	s_waitcnt lgkmcnt(3)
	v_mfma_f32_32x32x16_bf16 a[64:79], v[60:63], v[48:51], a[64:79]
	ds_read_b128 v[86:89], v83 offset:0x800
	v_mfma_f32_32x32x16_bf16 a[80:95], v[60:63], v[44:47], a[80:95]
	s_waitcnt lgkmcnt(3)
	v_mfma_f32_32x32x16_bf16 a[96:111], v[56:59], v[48:51], a[96:111]
	ds_read_b128 v[90:93], v81 offset:0
	v_mfma_f32_32x32x16_bf16 a[112:127], v[56:59], v[44:47], a[112:127]
	s_waitcnt vmcnt(5)
	ds_write_b128 v84, v[4:7] offset:0x8000
	s_waitcnt lgkmcnt(4)
	v_mfma_f32_32x32x16_bf16 a[16:31], v[52:55], v[48:51], a[16:31]
	ds_read_b128 v[94:97], v81 offset:0x800
	s_min_u32 s4, s4, 0xa80
	s_lshl_b32 s78, s4, 1
	s_waitcnt vmcnt(4)
	ds_write_b128 v84, v[8:11] offset:0x9000
	v_mfma_f32_32x32x16_bf16 a[0:15], v[52:55], v[44:47], a[0:15]
	ds_read_b128 v[98:101], v81 offset:0x1000
	s_add_i32 s6, s78, 0xc0
	s_mov_b32 s7, s79
	s_waitcnt vmcnt(3)
	ds_write_b128 v84, v[12:15] offset:0xa000
	s_waitcnt lgkmcnt(5)
	v_mfma_f32_32x32x16_bf16 a[32:47], v[90:93], v[40:43], a[32:47]
	ds_read_b128 v[102:105], v81 offset:0x1800
	s_add_i32 s3, s3, 2
	s_cmpk_lt_u32 s3, 0x56
	s_waitcnt vmcnt(2)
	ds_write_b128 v84, v[16:19] offset:0xb000
	v_mfma_f32_32x32x16_bf16 a[48:63], v[90:93], v[86:89], a[48:63]
	s_waitcnt vmcnt(1)
	ds_write_b128 v84, v[20:23] offset:0xc000
	s_waitcnt lgkmcnt(6)
	v_mfma_f32_32x32x16_bf16 a[64:79], v[94:97], v[40:43], a[64:79]
	s_waitcnt vmcnt(0)
	ds_write_b128 v84, v[24:27] offset:0xd000
	v_mfma_f32_32x32x16_bf16 a[80:95], v[94:97], v[86:89], a[80:95]
	s_waitcnt lgkmcnt(0)
	s_barrier
	ds_read_b128 v[44:47], v82 offset:0x8000
	ds_read_b128 v[48:51], v82 offset:0x8800
	ds_read_b128 v[52:55], v80 offset:0x8000
	v_mfma_f32_32x32x16_bf16 a[96:111], v[98:101], v[40:43], a[96:111]
	ds_read_b128 v[56:59], v80 offset:0x8800
	v_mfma_f32_32x32x16_bf16 a[112:127], v[98:101], v[86:89], a[112:127]
	ds_read_b128 v[60:63], v80 offset:0x9000
	v_mfma_f32_32x32x16_bf16 a[16:31], v[102:105], v[40:43], a[16:31]
	ds_read_b128 v[64:67], v80 offset:0x9800
	v_mfma_f32_32x32x16_bf16 a[0:15], v[102:105], v[86:89], a[0:15]
	s_waitcnt lgkmcnt(3)
	v_mfma_f32_32x32x16_bf16 a[32:47], v[52:55], v[44:47], a[32:47]
	ds_read_b128 v[40:43], v83 offset:0x8000
	v_mfma_f32_32x32x16_bf16 a[48:63], v[52:55], v[48:51], a[48:63]
	s_waitcnt lgkmcnt(3)
	v_mfma_f32_32x32x16_bf16 a[64:79], v[56:59], v[44:47], a[64:79]
	ds_read_b128 v[128:131], v83 offset:0x8800
	v_mfma_f32_32x32x16_bf16 a[80:95], v[56:59], v[48:51], a[80:95]
	s_waitcnt lgkmcnt(3)
	v_mfma_f32_32x32x16_bf16 a[96:111], v[60:63], v[44:47], a[96:111]
	ds_read_b128 v[86:89], v81 offset:0x8000
	v_mfma_f32_32x32x16_bf16 a[112:127], v[60:63], v[48:51], a[112:127]
	s_waitcnt lgkmcnt(3)
	v_mfma_f32_32x32x16_bf16 a[16:31], v[64:67], v[44:47], a[16:31]
	ds_read_b128 v[90:93], v81 offset:0x8800
	v_mfma_f32_32x32x16_bf16 a[0:15], v[64:67], v[48:51], a[0:15]
	ds_read_b128 v[94:97], v81 offset:0x9000
	s_waitcnt lgkmcnt(2)
	v_mfma_f32_32x32x16_bf16 a[32:47], v[86:89], v[40:43], a[32:47]
	ds_read_b128 v[132:135], v81 offset:0x9800
	v_mfma_f32_32x32x16_bf16 a[48:63], v[86:89], v[128:131], a[48:63]
	s_waitcnt lgkmcnt(2)
	v_mfma_f32_32x32x16_bf16 a[64:79], v[90:93], v[40:43], a[64:79]
	v_mfma_f32_32x32x16_bf16 a[80:95], v[90:93], v[128:131], a[80:95]
	s_waitcnt lgkmcnt(0)
	s_barrier
	v_mfma_f32_32x32x16_bf16 a[96:111], v[94:97], v[40:43], a[96:111]
	v_mfma_f32_32x32x16_bf16 a[112:127], v[94:97], v[128:131], a[112:127]
	s_nop 7
	s_nop 3
	s_branch .LBB0_139

.Lrs0_top:
	s_add_i32 s5, s4, 64
	s_min_u32 s6, s5, 0x3e0
	s_lshl_b32 s78, s6, 1
	ds_read_b128 v[44:47], v116 offset:0
	ds_read_b128 v[40:43], v116 offset:0x800
	ds_read_b128 v[36:39], v116 offset:0x1000
	ds_read_b128 v[92:95], v110 offset:0
	v_mfma_f32_32x32x16_bf16 a[144:159], v[136:139], v[80:83], a[144:159]
	ds_read_b128 v[88:91], v110 offset:0x800
	v_mfma_f32_32x32x16_bf16 a[160:175], v[136:139], v[112:115], a[160:175]
	ds_read_b128 v[84:87], v110 offset:0x1000
	v_lshl_add_u64 v[52:53], v[96:97], 0, s[78:79]
	global_load_dwordx4 v[56:59], v[52:53], off
	v_mfma_f32_32x32x16_bf16 a[176:191], v[136:139], v[128:131], a[176:191]
	ds_read_b128 v[48:51], v110 offset:0x1800
	v_lshl_add_u64 v[54:55], v[100:101], 0, s[78:79]
	global_load_dwordx4 v[52:55], v[54:55], off
	v_mfma_f32_32x32x16_bf16 a[32:47], v[132:135], v[80:83], a[32:47]
	v_lshl_add_u64 v[60:61], v[102:103], 0, s[78:79]
	global_load_dwordx4 v[64:67], v[60:61], off
	v_mfma_f32_32x32x16_bf16 a[16:31], v[132:135], v[112:115], a[16:31]
	v_lshl_add_u64 v[62:63], v[104:105], 0, s[78:79]
	global_load_dwordx4 v[60:63], v[62:63], off
	v_mfma_f32_32x32x16_bf16 a[0:15], v[132:135], v[128:131], a[0:15]
	v_lshl_add_u64 v[68:69], v[98:99], 0, s[78:79]
	global_load_dwordx4 v[76:79], v[68:69], off
	s_waitcnt lgkmcnt(3)
	v_mfma_f32_32x32x16_bf16 a[80:95], v[92:95], v[44:47], a[80:95]
	ds_read_b128 v[80:83], v117 offset:0
	v_mfma_f32_32x32x16_bf16 a[48:63], v[92:95], v[40:43], a[48:63]
	v_lshl_add_u64 v[70:71], v[106:107], 0, s[78:79]
	global_load_dwordx4 v[68:71], v[70:71], off
	v_mfma_f32_32x32x16_bf16 a[64:79], v[92:95], v[36:39], a[64:79]
	ds_read_b128 v[112:115], v117 offset:0x800
	s_waitcnt lgkmcnt(4)
	v_mfma_f32_32x32x16_bf16 a[96:111], v[88:91], v[44:47], a[96:111]
	v_lshl_add_u64 v[72:73], v[108:109], 0, s[78:79]
	global_load_dwordx4 v[72:75], v[72:73], off
	v_mfma_f32_32x32x16_bf16 a[112:127], v[88:91], v[40:43], a[112:127]
	ds_read_b128 v[120:123], v117 offset:0x1000
	s_min_u32 s4, s4, 0x380
	s_lshl_b32 s78, s4, 1
	v_mfma_f32_32x32x16_bf16 a[128:143], v[88:91], v[36:39], a[128:143]
	ds_read_b128 v[124:127], v111 offset:0
	s_add_i32 s6, s78, 0xc0
	s_mov_b32 s7, s79
	s_waitcnt lgkmcnt(5)
	v_mfma_f32_32x32x16_bf16 a[144:159], v[84:87], v[44:47], a[144:159]
	ds_read_b128 v[128:131], v111 offset:0x800
	s_add_i32 s3, s3, 2
	s_cmp_lt_u32 s3, 28
	v_mfma_f32_32x32x16_bf16 a[160:175], v[84:87], v[40:43], a[160:175]
	ds_read_b128 v[132:135], v111 offset:0x1000
	s_waitcnt vmcnt(13)
	ds_write_b128 v118, v[4:7] offset:0x8000
	v_mfma_f32_32x32x16_bf16 a[176:191], v[84:87], v[36:39], a[176:191]
	ds_read_b128 v[136:139], v111 offset:0x1800
	s_waitcnt vmcnt(12)
	ds_write_b128 v118, v[8:11] offset:0x9000
	s_waitcnt lgkmcnt(9)
	v_mfma_f32_32x32x16_bf16 a[32:47], v[48:51], v[44:47], a[32:47]
	s_waitcnt vmcnt(11)
	ds_write_b128 v118, v[12:15] offset:0xa000
	v_mfma_f32_32x32x16_bf16 a[16:31], v[48:51], v[40:43], a[16:31]
	s_waitcnt vmcnt(10)
	ds_write_b128 v118, v[16:19] offset:0xb000
	v_mfma_f32_32x32x16_bf16 a[0:15], v[48:51], v[36:39], a[0:15]
	s_waitcnt vmcnt(9)
	ds_write_b128 v118, v[20:23] offset:0xc000
	s_waitcnt lgkmcnt(8)
	v_mfma_f32_32x32x16_bf16 a[80:95], v[124:127], v[80:83], a[80:95]
	s_waitcnt vmcnt(8)
	ds_write_b128 v118, v[24:27] offset:0xd000
	v_mfma_f32_32x32x16_bf16 a[48:63], v[124:127], v[112:115], a[48:63]
	s_waitcnt vmcnt(7)
	ds_write_b128 v118, v[28:31] offset:0xe000
	v_mfma_f32_32x32x16_bf16 a[64:79], v[124:127], v[120:123], a[64:79]
	v_lshl_add_u64 v[4:5], v[96:97], 0, s[78:79]
	v_lshl_add_u64 v[8:9], v[100:101], 0, s[6:7]
	s_waitcnt lgkmcnt(9)
	v_mfma_f32_32x32x16_bf16 a[96:111], v[128:131], v[80:83], a[96:111]
	v_lshl_add_u64 v[12:13], v[102:103], 0, s[6:7]
	v_lshl_add_u64 v[16:17], v[104:105], 0, s[6:7]
	v_mfma_f32_32x32x16_bf16 a[112:127], v[128:131], v[112:115], a[112:127]
	v_lshl_add_u64 v[20:21], v[98:99], 0, s[78:79]
	v_lshl_add_u64 v[24:25], v[106:107], 0, s[6:7]
	v_mfma_f32_32x32x16_bf16 a[128:143], v[128:131], v[120:123], a[128:143]
	v_lshl_add_u64 v[28:29], v[108:109], 0, s[6:7]
	s_waitcnt lgkmcnt(0)
	s_barrier
	ds_read_b128 v[36:39], v116 offset:0x8000
	ds_read_b128 v[40:43], v116 offset:0x8800
	ds_read_b128 v[44:47], v116 offset:0x9000
	ds_read_b128 v[48:51], v110 offset:0x8000
	v_mfma_f32_32x32x16_bf16 a[144:159], v[132:135], v[80:83], a[144:159]
	ds_read_b128 v[84:87], v110 offset:0x8800
	v_mfma_f32_32x32x16_bf16 a[160:175], v[132:135], v[112:115], a[160:175]
	ds_read_b128 v[88:91], v110 offset:0x9000
	global_load_dwordx4 v[4:7], v[4:5], off offset:192
	v_mfma_f32_32x32x16_bf16 a[176:191], v[132:135], v[120:123], a[176:191]
	ds_read_b128 v[92:95], v110 offset:0x9800
	global_load_dwordx4 v[8:11], v[8:9], off
	v_mfma_f32_32x32x16_bf16 a[32:47], v[136:139], v[80:83], a[32:47]
	global_load_dwordx4 v[12:15], v[12:13], off
	v_mfma_f32_32x32x16_bf16 a[16:31], v[136:139], v[112:115], a[16:31]
	global_load_dwordx4 v[16:19], v[16:17], off
	v_mfma_f32_32x32x16_bf16 a[0:15], v[136:139], v[120:123], a[0:15]
	global_load_dwordx4 v[20:23], v[20:21], off offset:192
	s_waitcnt lgkmcnt(3)
	v_mfma_f32_32x32x16_bf16 a[80:95], v[48:51], v[36:39], a[80:95]
	ds_read_b128 v[80:83], v117 offset:0x8000
	v_mfma_f32_32x32x16_bf16 a[48:63], v[48:51], v[40:43], a[48:63]
	global_load_dwordx4 v[24:27], v[24:25], off
	v_mfma_f32_32x32x16_bf16 a[64:79], v[48:51], v[44:47], a[64:79]
	ds_read_b128 v[112:115], v117 offset:0x8800
	s_waitcnt lgkmcnt(4)
	v_mfma_f32_32x32x16_bf16 a[96:111], v[84:87], v[36:39], a[96:111]
	global_load_dwordx4 v[28:31], v[28:29], off
	v_mfma_f32_32x32x16_bf16 a[112:127], v[84:87], v[40:43], a[112:127]
	ds_read_b128 v[128:131], v117 offset:0x9000
	v_mfma_f32_32x32x16_bf16 a[128:143], v[84:87], v[44:47], a[128:143]
	ds_read_b128 v[120:123], v111 offset:0x8000
	s_waitcnt lgkmcnt(5)
	v_mfma_f32_32x32x16_bf16 a[144:159], v[88:91], v[36:39], a[144:159]
	ds_read_b128 v[124:127], v111 offset:0x8800
	v_mfma_f32_32x32x16_bf16 a[160:175], v[88:91], v[40:43], a[160:175]
	ds_read_b128 v[136:139], v111 offset:0x9000
	v_mfma_f32_32x32x16_bf16 a[176:191], v[88:91], v[44:47], a[176:191]
	ds_read_b128 v[132:135], v111 offset:0x9800
	s_waitcnt lgkmcnt(7)
	v_mfma_f32_32x32x16_bf16 a[32:47], v[92:95], v[36:39], a[32:47]
	s_waitcnt vmcnt(13)
	ds_write_b128 v118, v[56:59] offset:0
	v_mfma_f32_32x32x16_bf16 a[16:31], v[92:95], v[40:43], a[16:31]
	s_waitcnt vmcnt(12)
	ds_write_b128 v118, v[52:55] offset:0x1000
	v_mfma_f32_32x32x16_bf16 a[0:15], v[92:95], v[44:47], a[0:15]
	s_waitcnt vmcnt(11)
	ds_write_b128 v118, v[64:67] offset:0x2000
	s_waitcnt lgkmcnt(6)
	v_mfma_f32_32x32x16_bf16 a[80:95], v[120:123], v[80:83], a[80:95]
	s_waitcnt vmcnt(10)
	ds_write_b128 v118, v[60:63] offset:0x3000
	v_mfma_f32_32x32x16_bf16 a[48:63], v[120:123], v[112:115], a[48:63]
	s_waitcnt vmcnt(9)
	ds_write_b128 v118, v[76:79] offset:0x4000
	v_mfma_f32_32x32x16_bf16 a[64:79], v[120:123], v[128:131], a[64:79]
	s_waitcnt vmcnt(8)
	ds_write_b128 v118, v[68:71] offset:0x5000
	s_waitcnt lgkmcnt(8)
	v_mfma_f32_32x32x16_bf16 a[96:111], v[124:127], v[80:83], a[96:111]
	s_waitcnt vmcnt(7)
	ds_write_b128 v118, v[72:75] offset:0x6000
	v_mfma_f32_32x32x16_bf16 a[112:127], v[124:127], v[112:115], a[112:127]
	v_mfma_f32_32x32x16_bf16 a[128:143], v[124:127], v[128:131], a[128:143]
	s_waitcnt lgkmcnt(0)
	s_barrier
	s_cbranch_scc0 .Lrs0_last
	s_mov_b32 s4, s5
	s_branch .Lrs0_top
.Lrs0_last:
	s_mov_b32 s4, s5
	s_add_i32 s5, s4, 64
	s_min_u32 s6, s5, 0x3e0
	s_lshl_b32 s78, s6, 1
	ds_read_b128 v[44:47], v116 offset:0
	ds_read_b128 v[40:43], v116 offset:0x800
	ds_read_b128 v[36:39], v116 offset:0x1000
	ds_read_b128 v[92:95], v110 offset:0
	v_mfma_f32_32x32x16_bf16 a[144:159], v[136:139], v[80:83], a[144:159]
	ds_read_b128 v[88:91], v110 offset:0x800
	v_mfma_f32_32x32x16_bf16 a[160:175], v[136:139], v[112:115], a[160:175]
	ds_read_b128 v[84:87], v110 offset:0x1000
	v_mfma_f32_32x32x16_bf16 a[176:191], v[136:139], v[128:131], a[176:191]
	ds_read_b128 v[48:51], v110 offset:0x1800
	v_mfma_f32_32x32x16_bf16 a[32:47], v[132:135], v[80:83], a[32:47]
	v_mfma_f32_32x32x16_bf16 a[16:31], v[132:135], v[112:115], a[16:31]
	v_mfma_f32_32x32x16_bf16 a[0:15], v[132:135], v[128:131], a[0:15]
	s_waitcnt lgkmcnt(3)
	v_mfma_f32_32x32x16_bf16 a[80:95], v[92:95], v[44:47], a[80:95]
	ds_read_b128 v[80:83], v117 offset:0
	v_mfma_f32_32x32x16_bf16 a[48:63], v[92:95], v[40:43], a[48:63]
	v_mfma_f32_32x32x16_bf16 a[64:79], v[92:95], v[36:39], a[64:79]
	ds_read_b128 v[112:115], v117 offset:0x800
	s_waitcnt lgkmcnt(4)
	v_mfma_f32_32x32x16_bf16 a[96:111], v[88:91], v[44:47], a[96:111]
	v_mfma_f32_32x32x16_bf16 a[112:127], v[88:91], v[40:43], a[112:127]
	ds_read_b128 v[120:123], v117 offset:0x1000
	s_min_u32 s4, s4, 0x380
	s_lshl_b32 s78, s4, 1
	v_mfma_f32_32x32x16_bf16 a[128:143], v[88:91], v[36:39], a[128:143]
	ds_read_b128 v[124:127], v111 offset:0
	s_add_i32 s6, s78, 0xc0
	s_mov_b32 s7, s79
	s_waitcnt lgkmcnt(5)
	v_mfma_f32_32x32x16_bf16 a[144:159], v[84:87], v[44:47], a[144:159]
	ds_read_b128 v[128:131], v111 offset:0x800
	s_add_i32 s3, s3, 2
	s_cmp_lt_u32 s3, 30
	v_mfma_f32_32x32x16_bf16 a[160:175], v[84:87], v[40:43], a[160:175]
	ds_read_b128 v[132:135], v111 offset:0x1000
	s_waitcnt vmcnt(6)
	ds_write_b128 v118, v[4:7] offset:0x8000
	v_mfma_f32_32x32x16_bf16 a[176:191], v[84:87], v[36:39], a[176:191]
	ds_read_b128 v[136:139], v111 offset:0x1800
	s_waitcnt vmcnt(5)
	ds_write_b128 v118, v[8:11] offset:0x9000
	s_waitcnt lgkmcnt(9)
	v_mfma_f32_32x32x16_bf16 a[32:47], v[48:51], v[44:47], a[32:47]
	s_waitcnt vmcnt(4)
	ds_write_b128 v118, v[12:15] offset:0xa000
	v_mfma_f32_32x32x16_bf16 a[16:31], v[48:51], v[40:43], a[16:31]
	s_waitcnt vmcnt(3)
	ds_write_b128 v118, v[16:19] offset:0xb000
	v_mfma_f32_32x32x16_bf16 a[0:15], v[48:51], v[36:39], a[0:15]
	s_waitcnt vmcnt(2)
	ds_write_b128 v118, v[20:23] offset:0xc000
	s_waitcnt lgkmcnt(8)
	v_mfma_f32_32x32x16_bf16 a[80:95], v[124:127], v[80:83], a[80:95]
	s_waitcnt vmcnt(1)
	ds_write_b128 v118, v[24:27] offset:0xd000
	v_mfma_f32_32x32x16_bf16 a[48:63], v[124:127], v[112:115], a[48:63]
	s_waitcnt vmcnt(0)
	ds_write_b128 v118, v[28:31] offset:0xe000
	v_mfma_f32_32x32x16_bf16 a[64:79], v[124:127], v[120:123], a[64:79]
	s_waitcnt lgkmcnt(9)
	v_mfma_f32_32x32x16_bf16 a[96:111], v[128:131], v[80:83], a[96:111]
	v_mfma_f32_32x32x16_bf16 a[112:127], v[128:131], v[112:115], a[112:127]
	v_mfma_f32_32x32x16_bf16 a[128:143], v[128:131], v[120:123], a[128:143]
	s_waitcnt lgkmcnt(0)
	s_barrier
	ds_read_b128 v[36:39], v116 offset:0x8000
	ds_read_b128 v[40:43], v116 offset:0x8800
	ds_read_b128 v[44:47], v116 offset:0x9000
	ds_read_b128 v[48:51], v110 offset:0x8000
	v_mfma_f32_32x32x16_bf16 a[144:159], v[132:135], v[80:83], a[144:159]
	ds_read_b128 v[84:87], v110 offset:0x8800
	v_mfma_f32_32x32x16_bf16 a[160:175], v[132:135], v[112:115], a[160:175]
	ds_read_b128 v[88:91], v110 offset:0x9000
	v_mfma_f32_32x32x16_bf16 a[176:191], v[132:135], v[120:123], a[176:191]
	ds_read_b128 v[92:95], v110 offset:0x9800
	v_mfma_f32_32x32x16_bf16 a[32:47], v[136:139], v[80:83], a[32:47]
	v_mfma_f32_32x32x16_bf16 a[16:31], v[136:139], v[112:115], a[16:31]
	v_mfma_f32_32x32x16_bf16 a[0:15], v[136:139], v[120:123], a[0:15]
	s_waitcnt lgkmcnt(3)
	v_mfma_f32_32x32x16_bf16 a[80:95], v[48:51], v[36:39], a[80:95]
	ds_read_b128 v[80:83], v117 offset:0x8000
	v_mfma_f32_32x32x16_bf16 a[48:63], v[48:51], v[40:43], a[48:63]
	v_mfma_f32_32x32x16_bf16 a[64:79], v[48:51], v[44:47], a[64:79]
	ds_read_b128 v[112:115], v117 offset:0x8800
	s_waitcnt lgkmcnt(4)
	v_mfma_f32_32x32x16_bf16 a[96:111], v[84:87], v[36:39], a[96:111]
	v_mfma_f32_32x32x16_bf16 a[112:127], v[84:87], v[40:43], a[112:127]
	ds_read_b128 v[128:131], v117 offset:0x9000
	v_mfma_f32_32x32x16_bf16 a[128:143], v[84:87], v[44:47], a[128:143]
	ds_read_b128 v[120:123], v111 offset:0x8000
	s_waitcnt lgkmcnt(5)
	v_mfma_f32_32x32x16_bf16 a[144:159], v[88:91], v[36:39], a[144:159]
	ds_read_b128 v[124:127], v111 offset:0x8800
	v_mfma_f32_32x32x16_bf16 a[160:175], v[88:91], v[40:43], a[160:175]
	ds_read_b128 v[136:139], v111 offset:0x9000
	v_mfma_f32_32x32x16_bf16 a[176:191], v[88:91], v[44:47], a[176:191]
	ds_read_b128 v[132:135], v111 offset:0x9800
	s_waitcnt lgkmcnt(7)
	v_mfma_f32_32x32x16_bf16 a[32:47], v[92:95], v[36:39], a[32:47]
	v_mfma_f32_32x32x16_bf16 a[16:31], v[92:95], v[40:43], a[16:31]
	v_mfma_f32_32x32x16_bf16 a[0:15], v[92:95], v[44:47], a[0:15]
	s_waitcnt lgkmcnt(3)
	v_mfma_f32_32x32x16_bf16 a[80:95], v[120:123], v[80:83], a[80:95]
	v_mfma_f32_32x32x16_bf16 a[48:63], v[120:123], v[112:115], a[48:63]
	v_mfma_f32_32x32x16_bf16 a[64:79], v[120:123], v[128:131], a[64:79]
	s_waitcnt lgkmcnt(2)
	v_mfma_f32_32x32x16_bf16 a[96:111], v[124:127], v[80:83], a[96:111]
	v_mfma_f32_32x32x16_bf16 a[112:127], v[124:127], v[112:115], a[112:127]
	v_mfma_f32_32x32x16_bf16 a[128:143], v[124:127], v[128:131], a[128:143]
	s_waitcnt lgkmcnt(0)
	s_barrier
	v_mfma_f32_32x32x16_bf16 a[144:159], v[136:139], v[80:83], a[144:159]
	v_mfma_f32_32x32x16_bf16 a[160:175], v[136:139], v[112:115], a[160:175]
	v_mfma_f32_32x32x16_bf16 a[176:191], v[136:139], v[128:131], a[176:191]
	s_nop 7
	s_nop 3
	s_branch .LBB0_160

.Lrs3_top:
	s_add_i32 s7, s6, 64
	s_min_u32 s8, s7, 0x3e0
	s_lshl_b32 s78, s8, 1
	ds_read_b128 v[52:55], v116 offset:0
	ds_read_b128 v[48:51], v116 offset:0x800
	ds_read_b128 v[44:47], v116 offset:0x1000
	ds_read_b128 v[96:99], v114 offset:0
	v_mfma_f32_32x32x16_bf16 a[144:159], v[128:131], v[40:43], a[144:159]
	ds_read_b128 v[92:95], v114 offset:0x800
	v_mfma_f32_32x32x16_bf16 a[160:175], v[128:131], v[36:39], a[160:175]
	ds_read_b128 v[88:91], v114 offset:0x1000
	v_lshl_add_u64 v[60:61], v[100:101], 0, s[78:79]
	global_load_dwordx4 v[64:67], v[60:61], off
	v_mfma_f32_32x32x16_bf16 a[176:191], v[128:131], v[194:197], a[176:191]
	ds_read_b128 v[56:59], v114 offset:0x1800
	v_lshl_add_u64 v[62:63], v[104:105], 0, s[78:79]
	global_load_dwordx4 v[60:63], v[62:63], off
	v_mfma_f32_32x32x16_bf16 a[32:47], v[198:201], v[40:43], a[32:47]
	v_lshl_add_u64 v[68:69], v[106:107], 0, s[78:79]
	global_load_dwordx4 v[72:75], v[68:69], off
	v_mfma_f32_32x32x16_bf16 a[16:31], v[198:201], v[36:39], a[16:31]
	v_lshl_add_u64 v[70:71], v[108:109], 0, s[78:79]
	global_load_dwordx4 v[68:71], v[70:71], off
	v_mfma_f32_32x32x16_bf16 a[0:15], v[198:201], v[194:197], a[0:15]
	v_lshl_add_u64 v[76:77], v[102:103], 0, s[78:79]
	global_load_dwordx4 v[84:87], v[76:77], off
	s_waitcnt lgkmcnt(3)
	v_mfma_f32_32x32x16_bf16 a[48:63], v[96:99], v[52:55], a[48:63]
	ds_read_b128 v[36:39], v117 offset:0
	v_mfma_f32_32x32x16_bf16 a[64:79], v[96:99], v[48:51], a[64:79]
	v_lshl_add_u64 v[78:79], v[110:111], 0, s[78:79]
	global_load_dwordx4 v[76:79], v[78:79], off
	v_mfma_f32_32x32x16_bf16 a[80:95], v[96:99], v[44:47], a[80:95]
	ds_read_b128 v[40:43], v117 offset:0x800
	s_waitcnt lgkmcnt(4)
	v_mfma_f32_32x32x16_bf16 a[96:111], v[92:95], v[52:55], a[96:111]
	v_lshl_add_u64 v[80:81], v[112:113], 0, s[78:79]
	global_load_dwordx4 v[80:83], v[80:81], off
	v_mfma_f32_32x32x16_bf16 a[112:127], v[92:95], v[48:51], a[112:127]
	ds_read_b128 v[120:123], v117 offset:0x1000
	s_min_u32 s6, s6, 0x380
	s_lshl_b32 s78, s6, 1
	v_mfma_f32_32x32x16_bf16 a[128:143], v[92:95], v[44:47], a[128:143]
	ds_read_b128 v[124:127], v115 offset:0
	s_add_i32 s8, s78, 0xc0
	s_mov_b32 s9, s79
	s_waitcnt lgkmcnt(5)
	v_mfma_f32_32x32x16_bf16 a[144:159], v[88:91], v[52:55], a[144:159]
	ds_read_b128 v[128:131], v115 offset:0x800
	s_add_i32 s5, s5, 2
	s_cmp_lt_u32 s5, 28
	v_mfma_f32_32x32x16_bf16 a[160:175], v[88:91], v[48:51], a[160:175]
	ds_read_b128 v[132:135], v115 offset:0x1000
	s_waitcnt vmcnt(13)
	ds_write_b128 v118, v[4:7] offset:0x8000
	v_mfma_f32_32x32x16_bf16 a[176:191], v[88:91], v[44:47], a[176:191]
	ds_read_b128 v[136:139], v115 offset:0x1800
	s_waitcnt vmcnt(12)
	ds_write_b128 v118, v[8:11] offset:0x9000
	s_waitcnt lgkmcnt(9)
	v_mfma_f32_32x32x16_bf16 a[32:47], v[56:59], v[52:55], a[32:47]
	s_waitcnt vmcnt(11)
	ds_write_b128 v118, v[12:15] offset:0xa000
	v_mfma_f32_32x32x16_bf16 a[16:31], v[56:59], v[48:51], a[16:31]
	s_waitcnt vmcnt(10)
	ds_write_b128 v118, v[16:19] offset:0xb000
	v_mfma_f32_32x32x16_bf16 a[0:15], v[56:59], v[44:47], a[0:15]
	s_waitcnt vmcnt(9)
	ds_write_b128 v118, v[20:23] offset:0xc000
	s_waitcnt lgkmcnt(8)
	v_mfma_f32_32x32x16_bf16 a[48:63], v[124:127], v[36:39], a[48:63]
	s_waitcnt vmcnt(8)
	ds_write_b128 v118, v[24:27] offset:0xd000
	v_mfma_f32_32x32x16_bf16 a[64:79], v[124:127], v[40:43], a[64:79]
	s_waitcnt vmcnt(7)
	ds_write_b128 v118, v[28:31] offset:0xe000
	v_mfma_f32_32x32x16_bf16 a[80:95], v[124:127], v[120:123], a[80:95]
	v_lshl_add_u64 v[4:5], v[100:101], 0, s[78:79]
	v_lshl_add_u64 v[8:9], v[104:105], 0, s[8:9]
	s_waitcnt lgkmcnt(9)
	v_mfma_f32_32x32x16_bf16 a[96:111], v[128:131], v[36:39], a[96:111]
	v_lshl_add_u64 v[12:13], v[106:107], 0, s[8:9]
	v_lshl_add_u64 v[16:17], v[108:109], 0, s[8:9]
	v_mfma_f32_32x32x16_bf16 a[112:127], v[128:131], v[40:43], a[112:127]
	v_lshl_add_u64 v[20:21], v[102:103], 0, s[78:79]
	v_lshl_add_u64 v[24:25], v[110:111], 0, s[8:9]
	v_mfma_f32_32x32x16_bf16 a[128:143], v[128:131], v[120:123], a[128:143]
	v_lshl_add_u64 v[28:29], v[112:113], 0, s[8:9]
	s_waitcnt lgkmcnt(0)
	s_barrier
	ds_read_b128 v[44:47], v116 offset:0x8000
	ds_read_b128 v[48:51], v116 offset:0x8800
	ds_read_b128 v[52:55], v116 offset:0x9000
	ds_read_b128 v[56:59], v114 offset:0x8000
	v_mfma_f32_32x32x16_bf16 a[144:159], v[132:135], v[36:39], a[144:159]
	ds_read_b128 v[88:91], v114 offset:0x8800
	v_mfma_f32_32x32x16_bf16 a[160:175], v[132:135], v[40:43], a[160:175]
	ds_read_b128 v[92:95], v114 offset:0x9000
	global_load_dwordx4 v[4:7], v[4:5], off offset:192
	v_mfma_f32_32x32x16_bf16 a[176:191], v[132:135], v[120:123], a[176:191]
	ds_read_b128 v[96:99], v114 offset:0x9800
	global_load_dwordx4 v[8:11], v[8:9], off
	v_mfma_f32_32x32x16_bf16 a[32:47], v[136:139], v[36:39], a[32:47]
	global_load_dwordx4 v[12:15], v[12:13], off
	v_mfma_f32_32x32x16_bf16 a[16:31], v[136:139], v[40:43], a[16:31]
	global_load_dwordx4 v[16:19], v[16:17], off
	v_mfma_f32_32x32x16_bf16 a[0:15], v[136:139], v[120:123], a[0:15]
	global_load_dwordx4 v[20:23], v[20:21], off offset:192
	s_waitcnt lgkmcnt(3)
	v_mfma_f32_32x32x16_bf16 a[48:63], v[56:59], v[44:47], a[48:63]
	ds_read_b128 v[40:43], v117 offset:0x8000
	v_mfma_f32_32x32x16_bf16 a[64:79], v[56:59], v[48:51], a[64:79]
	global_load_dwordx4 v[24:27], v[24:25], off
	v_mfma_f32_32x32x16_bf16 a[80:95], v[56:59], v[52:55], a[80:95]
	ds_read_b128 v[36:39], v117 offset:0x8800
	s_waitcnt lgkmcnt(4)
	v_mfma_f32_32x32x16_bf16 a[96:111], v[88:91], v[44:47], a[96:111]
	global_load_dwordx4 v[28:31], v[28:29], off
	v_mfma_f32_32x32x16_bf16 a[112:127], v[88:91], v[48:51], a[112:127]
	ds_read_b128 v[194:197], v117 offset:0x9000
	v_mfma_f32_32x32x16_bf16 a[128:143], v[88:91], v[52:55], a[128:143]
	ds_read_b128 v[120:123], v115 offset:0x8000
	s_waitcnt lgkmcnt(5)
	v_mfma_f32_32x32x16_bf16 a[144:159], v[92:95], v[44:47], a[144:159]
	ds_read_b128 v[124:127], v115 offset:0x8800
	v_mfma_f32_32x32x16_bf16 a[160:175], v[92:95], v[48:51], a[160:175]
	ds_read_b128 v[128:131], v115 offset:0x9000
	v_mfma_f32_32x32x16_bf16 a[176:191], v[92:95], v[52:55], a[176:191]
	ds_read_b128 v[198:201], v115 offset:0x9800
	s_waitcnt lgkmcnt(7)
	v_mfma_f32_32x32x16_bf16 a[32:47], v[96:99], v[44:47], a[32:47]
	s_waitcnt vmcnt(13)
	ds_write_b128 v118, v[64:67] offset:0
	v_mfma_f32_32x32x16_bf16 a[16:31], v[96:99], v[48:51], a[16:31]
	s_waitcnt vmcnt(12)
	ds_write_b128 v118, v[60:63] offset:0x1000
	v_mfma_f32_32x32x16_bf16 a[0:15], v[96:99], v[52:55], a[0:15]
	s_waitcnt vmcnt(11)
	ds_write_b128 v118, v[72:75] offset:0x2000
	s_waitcnt lgkmcnt(6)
	v_mfma_f32_32x32x16_bf16 a[48:63], v[120:123], v[40:43], a[48:63]
	s_waitcnt vmcnt(10)
	ds_write_b128 v118, v[68:71] offset:0x3000
	v_mfma_f32_32x32x16_bf16 a[64:79], v[120:123], v[36:39], a[64:79]
	s_waitcnt vmcnt(9)
	ds_write_b128 v118, v[84:87] offset:0x4000
	v_mfma_f32_32x32x16_bf16 a[80:95], v[120:123], v[194:197], a[80:95]
	s_waitcnt vmcnt(8)
	ds_write_b128 v118, v[76:79] offset:0x5000
	s_waitcnt lgkmcnt(8)
	v_mfma_f32_32x32x16_bf16 a[96:111], v[124:127], v[40:43], a[96:111]
	s_waitcnt vmcnt(7)
	ds_write_b128 v118, v[80:83] offset:0x6000
	v_mfma_f32_32x32x16_bf16 a[112:127], v[124:127], v[36:39], a[112:127]
	v_mfma_f32_32x32x16_bf16 a[128:143], v[124:127], v[194:197], a[128:143]
	s_waitcnt lgkmcnt(0)
	s_barrier
	s_cbranch_scc0 .Lrs3_last
	s_mov_b32 s6, s7
	s_branch .Lrs3_top
.Lrs3_last:
	s_mov_b32 s6, s7
	s_add_i32 s7, s6, 64
	s_min_u32 s8, s7, 0x3e0
	s_lshl_b32 s78, s8, 1
	ds_read_b128 v[52:55], v116 offset:0
	ds_read_b128 v[48:51], v116 offset:0x800
	ds_read_b128 v[44:47], v116 offset:0x1000
	ds_read_b128 v[96:99], v114 offset:0
	v_mfma_f32_32x32x16_bf16 a[144:159], v[128:131], v[40:43], a[144:159]
	ds_read_b128 v[92:95], v114 offset:0x800
	v_mfma_f32_32x32x16_bf16 a[160:175], v[128:131], v[36:39], a[160:175]
	ds_read_b128 v[88:91], v114 offset:0x1000
	v_mfma_f32_32x32x16_bf16 a[176:191], v[128:131], v[194:197], a[176:191]
	ds_read_b128 v[56:59], v114 offset:0x1800
	v_mfma_f32_32x32x16_bf16 a[32:47], v[198:201], v[40:43], a[32:47]
	v_mfma_f32_32x32x16_bf16 a[16:31], v[198:201], v[36:39], a[16:31]
	v_mfma_f32_32x32x16_bf16 a[0:15], v[198:201], v[194:197], a[0:15]
	s_waitcnt lgkmcnt(3)
	v_mfma_f32_32x32x16_bf16 a[48:63], v[96:99], v[52:55], a[48:63]
	ds_read_b128 v[36:39], v117 offset:0
	v_mfma_f32_32x32x16_bf16 a[64:79], v[96:99], v[48:51], a[64:79]
	v_mfma_f32_32x32x16_bf16 a[80:95], v[96:99], v[44:47], a[80:95]
	ds_read_b128 v[40:43], v117 offset:0x800
	s_waitcnt lgkmcnt(4)
	v_mfma_f32_32x32x16_bf16 a[96:111], v[92:95], v[52:55], a[96:111]
	v_mfma_f32_32x32x16_bf16 a[112:127], v[92:95], v[48:51], a[112:127]
	ds_read_b128 v[120:123], v117 offset:0x1000
	s_min_u32 s6, s6, 0x380
	s_lshl_b32 s78, s6, 1
	v_mfma_f32_32x32x16_bf16 a[128:143], v[92:95], v[44:47], a[128:143]
	ds_read_b128 v[124:127], v115 offset:0
	s_add_i32 s8, s78, 0xc0
	s_mov_b32 s9, s79
	s_waitcnt lgkmcnt(5)
	v_mfma_f32_32x32x16_bf16 a[144:159], v[88:91], v[52:55], a[144:159]
	ds_read_b128 v[128:131], v115 offset:0x800
	s_add_i32 s5, s5, 2
	s_cmp_lt_u32 s5, 30
	v_mfma_f32_32x32x16_bf16 a[160:175], v[88:91], v[48:51], a[160:175]
	ds_read_b128 v[132:135], v115 offset:0x1000
	s_waitcnt vmcnt(6)
	ds_write_b128 v118, v[4:7] offset:0x8000
	v_mfma_f32_32x32x16_bf16 a[176:191], v[88:91], v[44:47], a[176:191]
	ds_read_b128 v[136:139], v115 offset:0x1800
	s_waitcnt vmcnt(5)
	ds_write_b128 v118, v[8:11] offset:0x9000
	s_waitcnt lgkmcnt(9)
	v_mfma_f32_32x32x16_bf16 a[32:47], v[56:59], v[52:55], a[32:47]
	s_waitcnt vmcnt(4)
	ds_write_b128 v118, v[12:15] offset:0xa000
	v_mfma_f32_32x32x16_bf16 a[16:31], v[56:59], v[48:51], a[16:31]
	s_waitcnt vmcnt(3)
	ds_write_b128 v118, v[16:19] offset:0xb000
	v_mfma_f32_32x32x16_bf16 a[0:15], v[56:59], v[44:47], a[0:15]
	s_waitcnt vmcnt(2)
	ds_write_b128 v118, v[20:23] offset:0xc000
	s_waitcnt lgkmcnt(8)
	v_mfma_f32_32x32x16_bf16 a[48:63], v[124:127], v[36:39], a[48:63]
	s_waitcnt vmcnt(1)
	ds_write_b128 v118, v[24:27] offset:0xd000
	v_mfma_f32_32x32x16_bf16 a[64:79], v[124:127], v[40:43], a[64:79]
	s_waitcnt vmcnt(0)
	ds_write_b128 v118, v[28:31] offset:0xe000
	v_mfma_f32_32x32x16_bf16 a[80:95], v[124:127], v[120:123], a[80:95]
	s_waitcnt lgkmcnt(9)
	v_mfma_f32_32x32x16_bf16 a[96:111], v[128:131], v[36:39], a[96:111]
	v_mfma_f32_32x32x16_bf16 a[112:127], v[128:131], v[40:43], a[112:127]
	v_mfma_f32_32x32x16_bf16 a[128:143], v[128:131], v[120:123], a[128:143]
	s_waitcnt lgkmcnt(0)
	s_barrier
	ds_read_b128 v[44:47], v116 offset:0x8000
	ds_read_b128 v[48:51], v116 offset:0x8800
	ds_read_b128 v[52:55], v116 offset:0x9000
	ds_read_b128 v[56:59], v114 offset:0x8000
	v_mfma_f32_32x32x16_bf16 a[144:159], v[132:135], v[36:39], a[144:159]
	ds_read_b128 v[88:91], v114 offset:0x8800
	v_mfma_f32_32x32x16_bf16 a[160:175], v[132:135], v[40:43], a[160:175]
	ds_read_b128 v[92:95], v114 offset:0x9000
	v_mfma_f32_32x32x16_bf16 a[176:191], v[132:135], v[120:123], a[176:191]
	ds_read_b128 v[96:99], v114 offset:0x9800
	v_mfma_f32_32x32x16_bf16 a[32:47], v[136:139], v[36:39], a[32:47]
	v_mfma_f32_32x32x16_bf16 a[16:31], v[136:139], v[40:43], a[16:31]
	v_mfma_f32_32x32x16_bf16 a[0:15], v[136:139], v[120:123], a[0:15]
	s_waitcnt lgkmcnt(3)
	v_mfma_f32_32x32x16_bf16 a[48:63], v[56:59], v[44:47], a[48:63]
	ds_read_b128 v[40:43], v117 offset:0x8000
	v_mfma_f32_32x32x16_bf16 a[64:79], v[56:59], v[48:51], a[64:79]
	v_mfma_f32_32x32x16_bf16 a[80:95], v[56:59], v[52:55], a[80:95]
	ds_read_b128 v[36:39], v117 offset:0x8800
	s_waitcnt lgkmcnt(4)
	v_mfma_f32_32x32x16_bf16 a[96:111], v[88:91], v[44:47], a[96:111]
	v_mfma_f32_32x32x16_bf16 a[112:127], v[88:91], v[48:51], a[112:127]
	ds_read_b128 v[194:197], v117 offset:0x9000
	v_mfma_f32_32x32x16_bf16 a[128:143], v[88:91], v[52:55], a[128:143]
	ds_read_b128 v[120:123], v115 offset:0x8000
	s_waitcnt lgkmcnt(5)
	v_mfma_f32_32x32x16_bf16 a[144:159], v[92:95], v[44:47], a[144:159]
	ds_read_b128 v[124:127], v115 offset:0x8800
	v_mfma_f32_32x32x16_bf16 a[160:175], v[92:95], v[48:51], a[160:175]
	ds_read_b128 v[128:131], v115 offset:0x9000
	v_mfma_f32_32x32x16_bf16 a[176:191], v[92:95], v[52:55], a[176:191]
	ds_read_b128 v[198:201], v115 offset:0x9800
	s_waitcnt lgkmcnt(7)
	v_mfma_f32_32x32x16_bf16 a[32:47], v[96:99], v[44:47], a[32:47]
	v_mfma_f32_32x32x16_bf16 a[16:31], v[96:99], v[48:51], a[16:31]
	v_mfma_f32_32x32x16_bf16 a[0:15], v[96:99], v[52:55], a[0:15]
	s_waitcnt lgkmcnt(3)
	v_mfma_f32_32x32x16_bf16 a[48:63], v[120:123], v[40:43], a[48:63]
	v_mfma_f32_32x32x16_bf16 a[64:79], v[120:123], v[36:39], a[64:79]
	v_mfma_f32_32x32x16_bf16 a[80:95], v[120:123], v[194:197], a[80:95]
	s_waitcnt lgkmcnt(2)
	v_mfma_f32_32x32x16_bf16 a[96:111], v[124:127], v[40:43], a[96:111]
	v_mfma_f32_32x32x16_bf16 a[112:127], v[124:127], v[36:39], a[112:127]
	v_mfma_f32_32x32x16_bf16 a[128:143], v[124:127], v[194:197], a[128:143]
	s_waitcnt lgkmcnt(0)
	s_barrier
	v_mfma_f32_32x32x16_bf16 a[144:159], v[128:131], v[40:43], a[144:159]
	v_mfma_f32_32x32x16_bf16 a[160:175], v[128:131], v[36:39], a[160:175]
	v_mfma_f32_32x32x16_bf16 a[176:191], v[128:131], v[194:197], a[176:191]
	s_nop 7
	s_nop 3
	s_branch .LBB0_203

.Lrs4_top:
	s_add_i32 s5, s4, 64
	s_min_u32 s6, s5, 0x3e0
	s_lshl_b32 s78, s6, 1
	ds_read_b128 v[48:51], v82 offset:0
	ds_read_b128 v[44:47], v82 offset:0x800
	ds_read_b128 v[64:67], v80 offset:0
	v_mfma_f32_32x32x16_bf16 a[96:111], v[94:97], v[40:43], a[96:111]
	ds_read_b128 v[60:63], v80 offset:0x800
	v_mfma_f32_32x32x16_bf16 a[112:127], v[94:97], v[128:131], a[112:127]
	ds_read_b128 v[56:59], v80 offset:0x1000
	v_lshl_add_u64 v[106:107], v[68:69], 0, s[78:79]
	global_load_dwordx4 v[106:109], v[106:107], off
	v_mfma_f32_32x32x16_bf16 a[16:31], v[132:135], v[40:43], a[16:31]
	ds_read_b128 v[52:55], v80 offset:0x1800
	v_lshl_add_u64 v[110:111], v[72:73], 0, s[78:79]
	global_load_dwordx4 v[110:113], v[110:111], off
	v_mfma_f32_32x32x16_bf16 a[0:15], v[132:135], v[128:131], a[0:15]
	v_lshl_add_u64 v[114:115], v[74:75], 0, s[78:79]
	global_load_dwordx4 v[114:117], v[114:115], off
	s_waitcnt lgkmcnt(3)
	v_mfma_f32_32x32x16_bf16 a[32:47], v[64:67], v[48:51], a[32:47]
	ds_read_b128 v[40:43], v83 offset:0
	v_mfma_f32_32x32x16_bf16 a[48:63], v[64:67], v[44:47], a[48:63]
	v_lshl_add_u64 v[118:119], v[76:77], 0, s[78:79]
	global_load_dwordx4 v[118:121], v[118:119], off
	s_waitcnt lgkmcnt(3)
	v_mfma_f32_32x32x16_bf16 a[64:79], v[60:63], v[48:51], a[64:79]
	ds_read_b128 v[86:89], v83 offset:0x800
	v_mfma_f32_32x32x16_bf16 a[80:95], v[60:63], v[44:47], a[80:95]
	v_lshl_add_u64 v[122:123], v[70:71], 0, s[78:79]
	global_load_dwordx4 v[122:125], v[122:123], off
	s_waitcnt lgkmcnt(3)
	v_mfma_f32_32x32x16_bf16 a[96:111], v[56:59], v[48:51], a[96:111]
	ds_read_b128 v[90:93], v81 offset:0
	v_mfma_f32_32x32x16_bf16 a[112:127], v[56:59], v[44:47], a[112:127]
	v_lshl_add_u64 v[126:127], v[78:79], 0, s[78:79]
	global_load_dwordx4 v[140:143], v[126:127], off
	s_waitcnt vmcnt(11)
	ds_write_b128 v84, v[4:7] offset:0x8000
	s_waitcnt lgkmcnt(4)
	v_mfma_f32_32x32x16_bf16 a[16:31], v[52:55], v[48:51], a[16:31]
	ds_read_b128 v[94:97], v81 offset:0x800
	s_min_u32 s4, s4, 0x380
	s_lshl_b32 s78, s4, 1
	s_waitcnt vmcnt(10)
	ds_write_b128 v84, v[8:11] offset:0x9000
	v_mfma_f32_32x32x16_bf16 a[0:15], v[52:55], v[44:47], a[0:15]
	ds_read_b128 v[98:101], v81 offset:0x1000
	s_add_i32 s6, s78, 0xc0
	s_mov_b32 s7, s79
	s_waitcnt vmcnt(9)
	ds_write_b128 v84, v[12:15] offset:0xa000
	s_waitcnt lgkmcnt(5)
	v_mfma_f32_32x32x16_bf16 a[32:47], v[90:93], v[40:43], a[32:47]
	ds_read_b128 v[102:105], v81 offset:0x1800
	s_add_i32 s3, s3, 2
	s_cmp_lt_u32 s3, 28
	s_waitcnt vmcnt(8)
	ds_write_b128 v84, v[16:19] offset:0xb000
	v_mfma_f32_32x32x16_bf16 a[48:63], v[90:93], v[86:89], a[48:63]
	s_waitcnt vmcnt(7)
	ds_write_b128 v84, v[20:23] offset:0xc000
	s_waitcnt lgkmcnt(6)
	v_mfma_f32_32x32x16_bf16 a[64:79], v[94:97], v[40:43], a[64:79]
	s_waitcnt vmcnt(6)
	ds_write_b128 v84, v[24:27] offset:0xd000
	v_mfma_f32_32x32x16_bf16 a[80:95], v[94:97], v[86:89], a[80:95]
	v_lshl_add_u64 v[4:5], v[68:69], 0, s[78:79]
	v_lshl_add_u64 v[8:9], v[72:73], 0, s[6:7]
	v_lshl_add_u64 v[12:13], v[74:75], 0, s[6:7]
	v_lshl_add_u64 v[16:17], v[76:77], 0, s[6:7]
	v_lshl_add_u64 v[20:21], v[70:71], 0, s[78:79]
	v_lshl_add_u64 v[24:25], v[78:79], 0, s[6:7]
	s_waitcnt lgkmcnt(0)
	s_barrier
	ds_read_b128 v[44:47], v82 offset:0x8000
	ds_read_b128 v[48:51], v82 offset:0x8800
	ds_read_b128 v[52:55], v80 offset:0x8000
	v_mfma_f32_32x32x16_bf16 a[96:111], v[98:101], v[40:43], a[96:111]
	ds_read_b128 v[56:59], v80 offset:0x8800
	v_mfma_f32_32x32x16_bf16 a[112:127], v[98:101], v[86:89], a[112:127]
	ds_read_b128 v[60:63], v80 offset:0x9000
	global_load_dwordx4 v[4:7], v[4:5], off offset:192
	v_mfma_f32_32x32x16_bf16 a[16:31], v[102:105], v[40:43], a[16:31]
	ds_read_b128 v[64:67], v80 offset:0x9800
	global_load_dwordx4 v[8:11], v[8:9], off
	v_mfma_f32_32x32x16_bf16 a[0:15], v[102:105], v[86:89], a[0:15]
	global_load_dwordx4 v[12:15], v[12:13], off
	s_waitcnt lgkmcnt(3)
	v_mfma_f32_32x32x16_bf16 a[32:47], v[52:55], v[44:47], a[32:47]
	ds_read_b128 v[40:43], v83 offset:0x8000
	v_mfma_f32_32x32x16_bf16 a[48:63], v[52:55], v[48:51], a[48:63]
	global_load_dwordx4 v[16:19], v[16:17], off
	s_waitcnt lgkmcnt(3)
	v_mfma_f32_32x32x16_bf16 a[64:79], v[56:59], v[44:47], a[64:79]
	ds_read_b128 v[128:131], v83 offset:0x8800
	v_mfma_f32_32x32x16_bf16 a[80:95], v[56:59], v[48:51], a[80:95]
	global_load_dwordx4 v[20:23], v[20:21], off offset:192
	s_waitcnt lgkmcnt(3)
	v_mfma_f32_32x32x16_bf16 a[96:111], v[60:63], v[44:47], a[96:111]
	ds_read_b128 v[86:89], v81 offset:0x8000
	v_mfma_f32_32x32x16_bf16 a[112:127], v[60:63], v[48:51], a[112:127]
	global_load_dwordx4 v[24:27], v[24:25], off
	s_waitcnt vmcnt(11)
	ds_write_b128 v84, v[106:109] offset:0
	s_waitcnt lgkmcnt(4)
	v_mfma_f32_32x32x16_bf16 a[16:31], v[64:67], v[44:47], a[16:31]
	ds_read_b128 v[90:93], v81 offset:0x8800
	s_waitcnt vmcnt(10)
	ds_write_b128 v84, v[110:113] offset:0x1000
	v_mfma_f32_32x32x16_bf16 a[0:15], v[64:67], v[48:51], a[0:15]
	ds_read_b128 v[94:97], v81 offset:0x9000
	s_waitcnt vmcnt(9)
	ds_write_b128 v84, v[114:117] offset:0x2000
	s_waitcnt lgkmcnt(5)
	v_mfma_f32_32x32x16_bf16 a[32:47], v[86:89], v[40:43], a[32:47]
	ds_read_b128 v[132:135], v81 offset:0x9800
	s_waitcnt vmcnt(8)
	ds_write_b128 v84, v[118:121] offset:0x3000
	v_mfma_f32_32x32x16_bf16 a[48:63], v[86:89], v[128:131], a[48:63]
	s_waitcnt vmcnt(7)
	ds_write_b128 v84, v[122:125] offset:0x4000
	s_waitcnt lgkmcnt(6)
	v_mfma_f32_32x32x16_bf16 a[64:79], v[90:93], v[40:43], a[64:79]
	s_waitcnt vmcnt(6)
	ds_write_b128 v84, v[140:143] offset:0x5000
	v_mfma_f32_32x32x16_bf16 a[80:95], v[90:93], v[128:131], a[80:95]
	s_waitcnt lgkmcnt(0)
	s_barrier
	s_cbranch_scc0 .Lrs4_last
	s_mov_b32 s4, s5
	s_branch .Lrs4_top
.Lrs4_last:
	s_mov_b32 s4, s5
	s_add_i32 s5, s4, 64
	s_min_u32 s6, s5, 0x3e0
	s_lshl_b32 s78, s6, 1
	ds_read_b128 v[48:51], v82 offset:0
	ds_read_b128 v[44:47], v82 offset:0x800
	ds_read_b128 v[64:67], v80 offset:0
	v_mfma_f32_32x32x16_bf16 a[96:111], v[94:97], v[40:43], a[96:111]
	ds_read_b128 v[60:63], v80 offset:0x800
	v_mfma_f32_32x32x16_bf16 a[112:127], v[94:97], v[128:131], a[112:127]
	ds_read_b128 v[56:59], v80 offset:0x1000
	v_mfma_f32_32x32x16_bf16 a[16:31], v[132:135], v[40:43], a[16:31]
	ds_read_b128 v[52:55], v80 offset:0x1800
	v_mfma_f32_32x32x16_bf16 a[0:15], v[132:135], v[128:131], a[0:15]
	s_waitcnt lgkmcnt(3)
	v_mfma_f32_32x32x16_bf16 a[32:47], v[64:67], v[48:51], a[32:47]
	ds_read_b128 v[40:43], v83 offset:0
	v_mfma_f32_32x32x16_bf16 a[48:63], v[64:67], v[44:47], a[48:63]
	s_waitcnt lgkmcnt(3)
	v_mfma_f32_32x32x16_bf16 a[64:79], v[60:63], v[48:51], a[64:79]
	ds_read_b128 v[86:89], v83 offset:0x800
	v_mfma_f32_32x32x16_bf16 a[80:95], v[60:63], v[44:47], a[80:95]
	s_waitcnt lgkmcnt(3)
	v_mfma_f32_32x32x16_bf16 a[96:111], v[56:59], v[48:51], a[96:111]
	ds_read_b128 v[90:93], v81 offset:0
	v_mfma_f32_32x32x16_bf16 a[112:127], v[56:59], v[44:47], a[112:127]
	s_waitcnt vmcnt(5)
	ds_write_b128 v84, v[4:7] offset:0x8000
	s_waitcnt lgkmcnt(4)
	v_mfma_f32_32x32x16_bf16 a[16:31], v[52:55], v[48:51], a[16:31]
	ds_read_b128 v[94:97], v81 offset:0x800
	s_min_u32 s4, s4, 0x380
	s_lshl_b32 s78, s4, 1
	s_waitcnt vmcnt(4)
	ds_write_b128 v84, v[8:11] offset:0x9000
	v_mfma_f32_32x32x16_bf16 a[0:15], v[52:55], v[44:47], a[0:15]
	ds_read_b128 v[98:101], v81 offset:0x1000
	s_add_i32 s6, s78, 0xc0
	s_mov_b32 s7, s79
	s_waitcnt vmcnt(3)
	ds_write_b128 v84, v[12:15] offset:0xa000
	s_waitcnt lgkmcnt(5)
	v_mfma_f32_32x32x16_bf16 a[32:47], v[90:93], v[40:43], a[32:47]
	ds_read_b128 v[102:105], v81 offset:0x1800
	s_add_i32 s3, s3, 2
	s_cmp_lt_u32 s3, 30
	s_waitcnt vmcnt(2)
	ds_write_b128 v84, v[16:19] offset:0xb000
	v_mfma_f32_32x32x16_bf16 a[48:63], v[90:93], v[86:89], a[48:63]
	s_waitcnt vmcnt(1)
	ds_write_b128 v84, v[20:23] offset:0xc000
	s_waitcnt lgkmcnt(6)
	v_mfma_f32_32x32x16_bf16 a[64:79], v[94:97], v[40:43], a[64:79]
	s_waitcnt vmcnt(0)
	ds_write_b128 v84, v[24:27] offset:0xd000
	v_mfma_f32_32x32x16_bf16 a[80:95], v[94:97], v[86:89], a[80:95]
	s_waitcnt lgkmcnt(0)
	s_barrier
	ds_read_b128 v[44:47], v82 offset:0x8000
	ds_read_b128 v[48:51], v82 offset:0x8800
	ds_read_b128 v[52:55], v80 offset:0x8000
	v_mfma_f32_32x32x16_bf16 a[96:111], v[98:101], v[40:43], a[96:111]
	ds_read_b128 v[56:59], v80 offset:0x8800
	v_mfma_f32_32x32x16_bf16 a[112:127], v[98:101], v[86:89], a[112:127]
	ds_read_b128 v[60:63], v80 offset:0x9000
	v_mfma_f32_32x32x16_bf16 a[16:31], v[102:105], v[40:43], a[16:31]
	ds_read_b128 v[64:67], v80 offset:0x9800
	v_mfma_f32_32x32x16_bf16 a[0:15], v[102:105], v[86:89], a[0:15]
	s_waitcnt lgkmcnt(3)
	v_mfma_f32_32x32x16_bf16 a[32:47], v[52:55], v[44:47], a[32:47]
	ds_read_b128 v[40:43], v83 offset:0x8000
	v_mfma_f32_32x32x16_bf16 a[48:63], v[52:55], v[48:51], a[48:63]
	s_waitcnt lgkmcnt(3)
	v_mfma_f32_32x32x16_bf16 a[64:79], v[56:59], v[44:47], a[64:79]
	ds_read_b128 v[128:131], v83 offset:0x8800
	v_mfma_f32_32x32x16_bf16 a[80:95], v[56:59], v[48:51], a[80:95]
	s_waitcnt lgkmcnt(3)
	v_mfma_f32_32x32x16_bf16 a[96:111], v[60:63], v[44:47], a[96:111]
	ds_read_b128 v[86:89], v81 offset:0x8000
	v_mfma_f32_32x32x16_bf16 a[112:127], v[60:63], v[48:51], a[112:127]
	s_waitcnt lgkmcnt(3)
	v_mfma_f32_32x32x16_bf16 a[16:31], v[64:67], v[44:47], a[16:31]
	ds_read_b128 v[90:93], v81 offset:0x8800
	v_mfma_f32_32x32x16_bf16 a[0:15], v[64:67], v[48:51], a[0:15]
	ds_read_b128 v[94:97], v81 offset:0x9000
	s_waitcnt lgkmcnt(2)
	v_mfma_f32_32x32x16_bf16 a[32:47], v[86:89], v[40:43], a[32:47]
	ds_read_b128 v[132:135], v81 offset:0x9800
	v_mfma_f32_32x32x16_bf16 a[48:63], v[86:89], v[128:131], a[48:63]
	s_waitcnt lgkmcnt(2)
	v_mfma_f32_32x32x16_bf16 a[64:79], v[90:93], v[40:43], a[64:79]
	v_mfma_f32_32x32x16_bf16 a[80:95], v[90:93], v[128:131], a[80:95]
	s_waitcnt lgkmcnt(0)
	s_barrier
	v_mfma_f32_32x32x16_bf16 a[96:111], v[94:97], v[40:43], a[96:111]
	v_mfma_f32_32x32x16_bf16 a[112:127], v[94:97], v[128:131], a[112:127]
	s_nop 7
	s_nop 3
	s_branch .LBB0_222

.Lrs5_top:
	s_add_i32 s4, s3, 64
	s_min_u32 s5, s4, 0x3e0
	s_lshl_b32 s78, s5, 1
	ds_read_b128 v[44:47], v78 offset:0
	ds_read_b128 v[40:43], v78 offset:0x800
	ds_read_b128 v[60:63], v76 offset:0
	v_mfma_f32_32x32x16_bf16 a[48:63], v[90:93], v[202:205], a[48:63]
	ds_read_b128 v[56:59], v76 offset:0x800
	v_mfma_f32_32x32x16_bf16 a[16:31], v[90:93], v[194:197], a[16:31]
	ds_read_b128 v[52:55], v76 offset:0x1000
	v_lshl_add_u64 v[106:107], v[64:65], 0, s[78:79]
	global_load_dwordx4 v[106:109], v[106:107], off
	v_mfma_f32_32x32x16_bf16 a[0:15], v[198:201], v[202:205], a[0:15]
	ds_read_b128 v[48:51], v76 offset:0x1800
	v_lshl_add_u64 v[110:111], v[68:69], 0, s[78:79]
	global_load_dwordx4 v[110:113], v[110:111], off
	v_mfma_f32_32x32x16_bf16 a[128:143], v[198:201], v[194:197], a[128:143]
	v_lshl_add_u64 v[114:115], v[70:71], 0, s[78:79]
	global_load_dwordx4 v[114:117], v[114:115], off
	s_waitcnt lgkmcnt(3)
	v_mfma_f32_32x32x16_bf16 a[112:127], v[60:63], v[44:47], a[112:127]
	ds_read_b128 v[82:85], v79 offset:0
	v_mfma_f32_32x32x16_bf16 a[96:111], v[60:63], v[40:43], a[96:111]
	v_lshl_add_u64 v[118:119], v[72:73], 0, s[78:79]
	global_load_dwordx4 v[118:121], v[118:119], off
	s_waitcnt lgkmcnt(3)
	v_mfma_f32_32x32x16_bf16 a[80:95], v[56:59], v[44:47], a[80:95]
	ds_read_b128 v[86:89], v79 offset:0x800
	v_mfma_f32_32x32x16_bf16 a[64:79], v[56:59], v[40:43], a[64:79]
	v_lshl_add_u64 v[122:123], v[66:67], 0, s[78:79]
	global_load_dwordx4 v[122:125], v[122:123], off
	s_waitcnt lgkmcnt(3)
	v_mfma_f32_32x32x16_bf16 a[48:63], v[52:55], v[44:47], a[48:63]
	ds_read_b128 v[90:93], v77 offset:0
	v_mfma_f32_32x32x16_bf16 a[16:31], v[52:55], v[40:43], a[16:31]
	v_lshl_add_u64 v[126:127], v[74:75], 0, s[78:79]
	global_load_dwordx4 v[126:129], v[126:127], off
	s_waitcnt vmcnt(11)
	ds_write_b128 v80, v[4:7] offset:0x8000
	s_waitcnt lgkmcnt(4)
	v_mfma_f32_32x32x16_bf16 a[0:15], v[48:51], v[44:47], a[0:15]
	ds_read_b128 v[94:97], v77 offset:0x800
	s_min_u32 s3, s3, 0x380
	s_lshl_b32 s78, s3, 1
	s_waitcnt vmcnt(10)
	ds_write_b128 v80, v[8:11] offset:0x9000
	v_mfma_f32_32x32x16_bf16 a[128:143], v[48:51], v[40:43], a[128:143]
	ds_read_b128 v[98:101], v77 offset:0x1000
	s_add_i32 s6, s78, 0xc0
	s_mov_b32 s7, s79
	s_waitcnt vmcnt(9)
	ds_write_b128 v80, v[12:15] offset:0xa000
	s_waitcnt lgkmcnt(5)
	v_mfma_f32_32x32x16_bf16 a[112:127], v[90:93], v[82:85], a[112:127]
	ds_read_b128 v[102:105], v77 offset:0x1800
	s_add_i32 s2, s2, 2
	s_cmp_gt_u32 s2, 27
	s_waitcnt vmcnt(8)
	ds_write_b128 v80, v[16:19] offset:0xb000
	v_mfma_f32_32x32x16_bf16 a[96:111], v[90:93], v[86:89], a[96:111]
	s_waitcnt vmcnt(7)
	ds_write_b128 v80, v[20:23] offset:0xc000
	s_waitcnt lgkmcnt(6)
	v_mfma_f32_32x32x16_bf16 a[80:95], v[94:97], v[82:85], a[80:95]
	s_waitcnt vmcnt(6)
	ds_write_b128 v80, v[24:27] offset:0xd000
	v_mfma_f32_32x32x16_bf16 a[64:79], v[94:97], v[86:89], a[64:79]
	v_lshl_add_u64 v[4:5], v[64:65], 0, s[78:79]
	v_lshl_add_u64 v[8:9], v[68:69], 0, s[6:7]
	v_lshl_add_u64 v[12:13], v[70:71], 0, s[6:7]
	v_lshl_add_u64 v[16:17], v[72:73], 0, s[6:7]
	v_lshl_add_u64 v[20:21], v[66:67], 0, s[78:79]
	v_lshl_add_u64 v[24:25], v[74:75], 0, s[6:7]
	s_waitcnt lgkmcnt(0)
	s_barrier
	ds_read_b128 v[40:43], v78 offset:0x8000
	ds_read_b128 v[44:47], v78 offset:0x8800
	ds_read_b128 v[48:51], v76 offset:0x8000
	v_mfma_f32_32x32x16_bf16 a[48:63], v[98:101], v[82:85], a[48:63]
	ds_read_b128 v[52:55], v76 offset:0x8800
	v_mfma_f32_32x32x16_bf16 a[16:31], v[98:101], v[86:89], a[16:31]
	ds_read_b128 v[56:59], v76 offset:0x9000
	global_load_dwordx4 v[4:7], v[4:5], off offset:192
	v_mfma_f32_32x32x16_bf16 a[0:15], v[102:105], v[82:85], a[0:15]
	ds_read_b128 v[60:63], v76 offset:0x9800
	global_load_dwordx4 v[8:11], v[8:9], off
	v_mfma_f32_32x32x16_bf16 a[128:143], v[102:105], v[86:89], a[128:143]
	global_load_dwordx4 v[12:15], v[12:13], off
	s_waitcnt lgkmcnt(3)
	v_mfma_f32_32x32x16_bf16 a[112:127], v[48:51], v[40:43], a[112:127]
	ds_read_b128 v[202:205], v79 offset:0x8000
	v_mfma_f32_32x32x16_bf16 a[96:111], v[48:51], v[44:47], a[96:111]
	global_load_dwordx4 v[16:19], v[16:17], off
	s_waitcnt lgkmcnt(3)
	v_mfma_f32_32x32x16_bf16 a[80:95], v[52:55], v[40:43], a[80:95]
	ds_read_b128 v[194:197], v79 offset:0x8800
	v_mfma_f32_32x32x16_bf16 a[64:79], v[52:55], v[44:47], a[64:79]
	global_load_dwordx4 v[20:23], v[20:21], off offset:192
	s_waitcnt lgkmcnt(3)
	v_mfma_f32_32x32x16_bf16 a[48:63], v[56:59], v[40:43], a[48:63]
	ds_read_b128 v[82:85], v77 offset:0x8000
	v_mfma_f32_32x32x16_bf16 a[16:31], v[56:59], v[44:47], a[16:31]
	global_load_dwordx4 v[24:27], v[24:25], off
	s_waitcnt vmcnt(11)
	ds_write_b128 v80, v[106:109] offset:0
	s_waitcnt lgkmcnt(4)
	v_mfma_f32_32x32x16_bf16 a[0:15], v[60:63], v[40:43], a[0:15]
	ds_read_b128 v[86:89], v77 offset:0x8800
	s_waitcnt vmcnt(10)
	ds_write_b128 v80, v[110:113] offset:0x1000
	v_mfma_f32_32x32x16_bf16 a[128:143], v[60:63], v[44:47], a[128:143]
	ds_read_b128 v[90:93], v77 offset:0x9000
	s_waitcnt vmcnt(9)
	ds_write_b128 v80, v[114:117] offset:0x2000
	s_waitcnt lgkmcnt(5)
	v_mfma_f32_32x32x16_bf16 a[112:127], v[82:85], v[202:205], a[112:127]
	ds_read_b128 v[198:201], v77 offset:0x9800
	s_waitcnt vmcnt(8)
	ds_write_b128 v80, v[118:121] offset:0x3000
	v_mfma_f32_32x32x16_bf16 a[96:111], v[82:85], v[194:197], a[96:111]
	s_waitcnt vmcnt(7)
	ds_write_b128 v80, v[122:125] offset:0x4000
	s_waitcnt lgkmcnt(6)
	v_mfma_f32_32x32x16_bf16 a[80:95], v[86:89], v[202:205], a[80:95]
	s_waitcnt vmcnt(6)
	ds_write_b128 v80, v[126:129] offset:0x5000
	v_mfma_f32_32x32x16_bf16 a[64:79], v[86:89], v[194:197], a[64:79]
	s_waitcnt lgkmcnt(0)
	s_barrier
	s_cbranch_scc1 .Lrs5_last
	s_mov_b32 s3, s4
	s_branch .Lrs5_top
.Lrs5_last:
	s_mov_b32 s3, s4
	s_add_i32 s4, s3, 64
	s_min_u32 s5, s4, 0x3e0
	s_lshl_b32 s78, s5, 1
	ds_read_b128 v[44:47], v78 offset:0
	ds_read_b128 v[40:43], v78 offset:0x800
	ds_read_b128 v[60:63], v76 offset:0
	v_mfma_f32_32x32x16_bf16 a[48:63], v[90:93], v[202:205], a[48:63]
	ds_read_b128 v[56:59], v76 offset:0x800
	v_mfma_f32_32x32x16_bf16 a[16:31], v[90:93], v[194:197], a[16:31]
	ds_read_b128 v[52:55], v76 offset:0x1000
	v_mfma_f32_32x32x16_bf16 a[0:15], v[198:201], v[202:205], a[0:15]
	ds_read_b128 v[48:51], v76 offset:0x1800
	v_mfma_f32_32x32x16_bf16 a[128:143], v[198:201], v[194:197], a[128:143]
	s_waitcnt lgkmcnt(3)
	v_mfma_f32_32x32x16_bf16 a[112:127], v[60:63], v[44:47], a[112:127]
	ds_read_b128 v[82:85], v79 offset:0
	v_mfma_f32_32x32x16_bf16 a[96:111], v[60:63], v[40:43], a[96:111]
	s_waitcnt lgkmcnt(3)
	v_mfma_f32_32x32x16_bf16 a[80:95], v[56:59], v[44:47], a[80:95]
	ds_read_b128 v[86:89], v79 offset:0x800
	v_mfma_f32_32x32x16_bf16 a[64:79], v[56:59], v[40:43], a[64:79]
	s_waitcnt lgkmcnt(3)
	v_mfma_f32_32x32x16_bf16 a[48:63], v[52:55], v[44:47], a[48:63]
	ds_read_b128 v[90:93], v77 offset:0
	v_mfma_f32_32x32x16_bf16 a[16:31], v[52:55], v[40:43], a[16:31]
	s_waitcnt vmcnt(5)
	ds_write_b128 v80, v[4:7] offset:0x8000
	s_waitcnt lgkmcnt(4)
	v_mfma_f32_32x32x16_bf16 a[0:15], v[48:51], v[44:47], a[0:15]
	ds_read_b128 v[94:97], v77 offset:0x800
	s_min_u32 s3, s3, 0x380
	s_lshl_b32 s78, s3, 1
	s_waitcnt vmcnt(4)
	ds_write_b128 v80, v[8:11] offset:0x9000
	v_mfma_f32_32x32x16_bf16 a[128:143], v[48:51], v[40:43], a[128:143]
	ds_read_b128 v[98:101], v77 offset:0x1000
	s_add_i32 s6, s78, 0xc0
	s_mov_b32 s7, s79
	s_waitcnt vmcnt(3)
	ds_write_b128 v80, v[12:15] offset:0xa000
	s_waitcnt lgkmcnt(5)
	v_mfma_f32_32x32x16_bf16 a[112:127], v[90:93], v[82:85], a[112:127]
	ds_read_b128 v[102:105], v77 offset:0x1800
	s_add_i32 s2, s2, 2
	s_cmp_gt_u32 s2, 29
	s_waitcnt vmcnt(2)
	ds_write_b128 v80, v[16:19] offset:0xb000
	v_mfma_f32_32x32x16_bf16 a[96:111], v[90:93], v[86:89], a[96:111]
	s_waitcnt vmcnt(1)
	ds_write_b128 v80, v[20:23] offset:0xc000
	s_waitcnt lgkmcnt(6)
	v_mfma_f32_32x32x16_bf16 a[80:95], v[94:97], v[82:85], a[80:95]
	s_waitcnt vmcnt(0)
	ds_write_b128 v80, v[24:27] offset:0xd000
	v_mfma_f32_32x32x16_bf16 a[64:79], v[94:97], v[86:89], a[64:79]
	s_waitcnt lgkmcnt(0)
	s_barrier
	ds_read_b128 v[40:43], v78 offset:0x8000
	ds_read_b128 v[44:47], v78 offset:0x8800
	ds_read_b128 v[48:51], v76 offset:0x8000
	v_mfma_f32_32x32x16_bf16 a[48:63], v[98:101], v[82:85], a[48:63]
	ds_read_b128 v[52:55], v76 offset:0x8800
	v_mfma_f32_32x32x16_bf16 a[16:31], v[98:101], v[86:89], a[16:31]
	ds_read_b128 v[56:59], v76 offset:0x9000
	v_mfma_f32_32x32x16_bf16 a[0:15], v[102:105], v[82:85], a[0:15]
	ds_read_b128 v[60:63], v76 offset:0x9800
	v_mfma_f32_32x32x16_bf16 a[128:143], v[102:105], v[86:89], a[128:143]
	s_waitcnt lgkmcnt(3)
	v_mfma_f32_32x32x16_bf16 a[112:127], v[48:51], v[40:43], a[112:127]
	ds_read_b128 v[202:205], v79 offset:0x8000
	v_mfma_f32_32x32x16_bf16 a[96:111], v[48:51], v[44:47], a[96:111]
	s_waitcnt lgkmcnt(3)
	v_mfma_f32_32x32x16_bf16 a[80:95], v[52:55], v[40:43], a[80:95]
	ds_read_b128 v[194:197], v79 offset:0x8800
	v_mfma_f32_32x32x16_bf16 a[64:79], v[52:55], v[44:47], a[64:79]
	s_waitcnt lgkmcnt(3)
	v_mfma_f32_32x32x16_bf16 a[48:63], v[56:59], v[40:43], a[48:63]
	ds_read_b128 v[82:85], v77 offset:0x8000
	v_mfma_f32_32x32x16_bf16 a[16:31], v[56:59], v[44:47], a[16:31]
	s_waitcnt lgkmcnt(3)
	v_mfma_f32_32x32x16_bf16 a[0:15], v[60:63], v[40:43], a[0:15]
	ds_read_b128 v[86:89], v77 offset:0x8800
	v_mfma_f32_32x32x16_bf16 a[128:143], v[60:63], v[44:47], a[128:143]
	ds_read_b128 v[90:93], v77 offset:0x9000
	s_waitcnt lgkmcnt(2)
	v_mfma_f32_32x32x16_bf16 a[112:127], v[82:85], v[202:205], a[112:127]
	ds_read_b128 v[198:201], v77 offset:0x9800
	v_mfma_f32_32x32x16_bf16 a[96:111], v[82:85], v[194:197], a[96:111]
	s_waitcnt lgkmcnt(2)
	v_mfma_f32_32x32x16_bf16 a[80:95], v[86:89], v[202:205], a[80:95]
	v_mfma_f32_32x32x16_bf16 a[64:79], v[86:89], v[194:197], a[64:79]
	s_waitcnt lgkmcnt(0)
	s_barrier
	v_mfma_f32_32x32x16_bf16 a[48:63], v[90:93], v[202:205], a[48:63]
	v_mfma_f32_32x32x16_bf16 a[16:31], v[90:93], v[194:197], a[16:31]
	s_nop 7
	s_nop 3
	s_branch .LBB0_777

.LBB0_1093:
	s_or_b64 exec, exec, s[0:1]
	s_lshl_b32 s2, s2, 4
	v_ashrrev_i32_e32 v8, 7, v4
	v_add_u32_e32 v0, s2, v8
	v_ashrrev_i32_e32 v1, 31, v0
	v_lshlrev_b64 v[0:1], 8, v[0:1]
	v_and_b32_e32 v16, 0xfc, v5
	v_or_b32_e32 v0, v0, v16
	v_lshl_add_u64 v[2:3], s[64:65], 0, v[0:1]
	v_lshl_add_u64 v[0:1], s[66:67], 0, v[0:1]
	s_waitcnt lgkmcnt(0)
	s_barrier
	global_load_dword v50, v[0:1], off
	global_load_dword v51, v[2:3], off
	v_add_u32_e32 v28, 0x100, v4
	v_ashrrev_i32_e32 v37, 7, v28
	v_add_u32_e32 v28, s2, v37
	v_ashrrev_i32_e32 v29, 31, v28
	v_lshlrev_b64 v[28:29], 8, v[28:29]
	v_or_b32_e32 v28, v28, v16
	v_lshl_add_u64 v[30:31], s[66:67], 0, v[28:29]
	global_load_dword v52, v[30:31], off
	v_add_u32_e32 v28, 0x100, v4
	v_ashrrev_i32_e32 v37, 7, v28
	v_add_u32_e32 v28, s2, v37
	v_ashrrev_i32_e32 v29, 31, v28
	v_lshlrev_b64 v[28:29], 8, v[28:29]
	v_or_b32_e32 v28, v28, v16
	v_lshl_add_u64 v[28:29], s[64:65], 0, v[28:29]
	global_load_dword v53, v[28:29], off
	v_add_u32_e32 v28, 0x200, v4
	v_ashrrev_i32_e32 v31, 7, v28
	v_add_u32_e32 v28, s2, v31
	v_ashrrev_i32_e32 v29, 31, v28
	v_lshlrev_b64 v[28:29], 8, v[28:29]
	v_or_b32_e32 v28, v28, v16
	v_lshl_add_u64 v[28:29], s[66:67], 0, v[28:29]
	global_load_dword v54, v[28:29], off
	v_add_u32_e32 v28, 0x200, v4
	v_ashrrev_i32_e32 v31, 7, v28
	v_add_u32_e32 v28, s2, v31
	v_ashrrev_i32_e32 v29, 31, v28
	v_lshlrev_b64 v[28:29], 8, v[28:29]
	v_or_b32_e32 v28, v28, v16
	v_lshl_add_u64 v[32:33], s[64:65], 0, v[28:29]
	global_load_dword v55, v[32:33], off
	v_add_u32_e32 v28, 0x300, v4
	v_ashrrev_i32_e32 v49, 7, v28
	v_add_u32_e32 v32, s2, v49
	v_ashrrev_i32_e32 v33, 31, v32
	v_lshlrev_b64 v[32:33], 8, v[32:33]
	v_or_b32_e32 v32, v32, v16
	v_lshl_add_u64 v[32:33], s[66:67], 0, v[32:33]
	global_load_dword v56, v[32:33], off
	v_add_u32_e32 v28, 0x300, v4
	v_ashrrev_i32_e32 v49, 7, v28
	v_add_u32_e32 v32, s2, v49
	v_ashrrev_i32_e32 v33, 31, v32
	v_lshlrev_b64 v[32:33], 8, v[32:33]
	v_or_b32_e32 v32, v32, v16
	v_lshl_add_u64 v[40:41], s[64:65], 0, v[32:33]
	global_load_dword v57, v[40:41], off
	v_add_u32_e32 v27, 0x400, v4
	v_ashrrev_i32_e32 v48, 7, v27
	v_add_u32_e32 v32, s2, v48
	v_ashrrev_i32_e32 v33, 31, v32
	v_lshlrev_b64 v[32:33], 8, v[32:33]
	v_or_b32_e32 v32, v32, v16
	v_lshl_add_u64 v[38:39], s[64:65], 0, v[32:33]
	global_load_dword v58, v[38:39], off
	v_add_u32_e32 v27, 0x400, v4
	v_ashrrev_i32_e32 v48, 7, v27
	v_add_u32_e32 v32, s2, v48
	v_ashrrev_i32_e32 v33, 31, v32
	v_lshlrev_b64 v[32:33], 8, v[32:33]
	v_or_b32_e32 v32, v32, v16
	v_lshl_add_u64 v[32:33], s[66:67], 0, v[32:33]
	global_load_dword v59, v[32:33], off
	v_add_u32_e32 v28, 0x500, v4
	v_ashrrev_i32_e32 v37, 7, v28
	v_add_u32_e32 v28, s2, v37
	v_ashrrev_i32_e32 v29, 31, v28
	v_lshlrev_b64 v[28:29], 8, v[28:29]
	v_or_b32_e32 v28, v28, v16
	v_lshl_add_u64 v[28:29], s[66:67], 0, v[28:29]
	global_load_dword v60, v[28:29], off
	v_add_u32_e32 v28, 0x500, v4
	v_ashrrev_i32_e32 v37, 7, v28
	v_add_u32_e32 v28, s2, v37
	v_ashrrev_i32_e32 v29, 31, v28
	v_lshlrev_b64 v[28:29], 8, v[28:29]
	v_or_b32_e32 v28, v28, v16
	v_lshl_add_u64 v[30:31], s[64:65], 0, v[28:29]
	global_load_dword v61, v[30:31], off
	v_add_u32_e32 v28, 0x600, v4
	v_ashrrev_i32_e32 v34, 7, v28
	v_add_u32_e32 v28, s2, v34
	v_ashrrev_i32_e32 v29, 31, v28
	v_lshlrev_b64 v[28:29], 8, v[28:29]
	v_or_b32_e32 v28, v28, v16
	v_lshl_add_u64 v[28:29], s[66:67], 0, v[28:29]
	global_load_dword v62, v[28:29], off
	v_add_u32_e32 v28, 0x600, v4
	v_ashrrev_i32_e32 v34, 7, v28
	v_add_u32_e32 v28, s2, v34
	v_ashrrev_i32_e32 v29, 31, v28
	v_lshlrev_b64 v[28:29], 8, v[28:29]
	v_or_b32_e32 v28, v28, v16
	v_lshl_add_u64 v[30:31], s[64:65], 0, v[28:29]
	global_load_dword v63, v[30:31], off
	v_add_u32_e32 v28, 0x700, v4
	v_ashrrev_i32_e32 v42, 7, v28
	v_add_u32_e32 v28, s2, v42
	v_ashrrev_i32_e32 v29, 31, v28
	v_lshlrev_b64 v[28:29], 8, v[28:29]
	v_or_b32_e32 v28, v28, v16
	v_lshl_add_u64 v[28:29], s[66:67], 0, v[28:29]
	global_load_dword v64, v[28:29], off
	v_add_u32_e32 v28, 0x700, v4
	v_ashrrev_i32_e32 v42, 7, v28
	v_add_u32_e32 v28, s2, v42
	v_ashrrev_i32_e32 v29, 31, v28
	v_lshlrev_b64 v[28:29], 8, v[28:29]
	v_or_b32_e32 v28, v28, v16
	v_lshl_add_u64 v[30:31], s[64:65], 0, v[28:29]
	global_load_dword v65, v[30:31], off
	s_waitcnt vmcnt(0)
	v_mov_b32_e32 v18, v50
	v_add_u32_e32 v0, 0x100, v4
	v_ashrrev_i32_e32 v9, 7, v0
	v_add_u32_e32 v0, s2, v9
	v_ashrrev_i32_e32 v1, 31, v0
	v_lshlrev_b64 v[0:1], 8, v[0:1]
	v_or_b32_e32 v0, v0, v16
	v_mov_b32_e32 v17, v51
	v_lshl_add_u64 v[2:3], s[66:67], 0, v[0:1]
	v_mov_b32_e32 v19, v52
	v_lshl_add_u64 v[0:1], s[64:65], 0, v[0:1]
	v_mov_b32_e32 v20, v53
	v_add_u32_e32 v2, 0x200, v4
	v_and_b32_e32 v192, 0xfe, v5
	v_ashrrev_i32_e32 v5, 7, v2
	v_add_u32_e32 v2, s2, v5
	v_ashrrev_i32_e32 v3, 31, v2
	v_lshlrev_b64 v[2:3], 8, v[2:3]
	v_or_b32_e32 v2, v2, v16
	v_lshl_add_u64 v[6:7], s[64:65], 0, v[2:3]
	v_lshl_add_u64 v[2:3], s[66:67], 0, v[2:3]
	v_mov_b32_e32 v21, v54
	v_mov_b32_e32 v22, v55
	v_and_b32_e32 v11, 0x7e, v4
	s_lshl_b32 s0, s5, 9
	s_lshl_b32 s1, s4, 4
	v_add_u32_e32 v2, 0x300, v4
	s_lshl_b32 s78, s3, 8
	v_add_u32_e32 v3, 0x400, v4
	v_lshlrev_b32_e32 v6, 2, v11
	s_or_b32 s3, s0, s1
	v_ashrrev_i32_e32 v23, 7, v2
	v_and_b32_e32 v10, 1, v4
	v_mov_b64_e32 v[0:1], s[90:91]
	v_ashrrev_i32_e32 v24, 7, v3
	ds_read_b64 v[2:3], v6
	v_add_u32_e32 v7, s3, v8
	v_add_u32_e32 v6, s2, v23
	v_cmp_eq_u32_e32 vcc, 0, v10
	v_mad_i64_i32 v[10:11], s[0:1], v7, s68, v[0:1]
	v_ashrrev_i32_e32 v7, 31, v6
	v_lshlrev_b64 v[6:7], 8, v[6:7]
	v_or_b32_e32 v6, v6, v16
	v_lshl_add_u64 v[14:15], s[64:65], 0, v[6:7]
	v_lshl_add_u64 v[6:7], s[66:67], 0, v[6:7]
	v_mov_b32_e32 v25, v56
	v_mov_b32_e32 v26, v57
	v_add_u32_e32 v9, s3, v9
	v_add_u32_e32 v8, s2, v24
	v_mad_i64_i32 v[12:13], s[0:1], v9, s68, v[0:1]
	v_ashrrev_i32_e32 v9, 31, v8
	v_lshl_add_u64 v[10:11], v[10:11], 0, s[78:79]
	v_lshlrev_b64 v[8:9], 8, v[8:9]
	v_lshl_add_u64 v[10:11], v[10:11], 0, v[192:193]
	v_or_b32_e32 v8, v8, v16
	s_mov_b32 s4, 0x1648000
	v_add_co_u32_e64 v6, s[0:1], s4, v10
	v_lshl_add_u64 v[14:15], s[64:65], 0, v[8:9]
	v_lshl_add_u64 v[8:9], s[66:67], 0, v[8:9]
	v_addc_co_u32_e64 v7, s[0:1], 0, v11, s[0:1]
	v_mov_b32_e32 v10, v58
	v_mov_b32_e32 v11, v59
	v_add_u32_e32 v5, s3, v5
	s_waitcnt lgkmcnt(0)
	v_mul_f32_e32 v8, v3, v18
	v_mul_f32_e32 v9, v2, v18
	v_fma_f32 v8, v2, v17, -v8
	v_fmac_f32_e32 v9, v3, v17
	v_mul_f32_e32 v14, v3, v19
	v_cndmask_b32_e64 v8, -v9, v8, vcc
	v_fma_f32 v9, v2, v20, -v14
	v_bfe_u32 v14, v8, 16, 1
	v_mul_f32_e32 v15, v2, v19
	v_add3_u32 v8, v8, v14, s80
	v_fmac_f32_e32 v15, v3, v20
	global_store_short_d16_hi v[6:7], v8, off offset:1024
	v_add_u32_e32 v6, 0x500, v4
	v_cndmask_b32_e64 v9, -v15, v9, vcc
	v_ashrrev_i32_e32 v15, 7, v6
	v_add_u32_e32 v6, s2, v15
	v_ashrrev_i32_e32 v7, 31, v6
	v_lshlrev_b64 v[6:7], 8, v[6:7]
	v_bfe_u32 v14, v9, 16, 1
	v_or_b32_e32 v6, v6, v16
	v_add3_u32 v14, v9, v14, s80
	v_lshl_add_u64 v[8:9], s[64:65], 0, v[6:7]
	v_lshl_add_u64 v[6:7], s[66:67], 0, v[6:7]
	v_mov_b32_e32 v17, v60
	v_mov_b32_e32 v18, v61
	v_lshl_add_u64 v[6:7], v[12:13], 0, s[78:79]
	v_lshl_add_u64 v[6:7], v[6:7], 0, v[192:193]
	v_add_co_u32_e64 v6, s[0:1], s4, v6
	s_nop 1
	v_addc_co_u32_e64 v7, s[0:1], 0, v7, s[0:1]
	global_store_short_d16_hi v[6:7], v14, off offset:1024
	v_add_u32_e32 v6, 0x600, v4
	v_ashrrev_i32_e32 v12, 7, v6
	v_add_u32_e32 v6, s2, v12
	v_ashrrev_i32_e32 v7, 31, v6
	v_lshlrev_b64 v[6:7], 8, v[6:7]
	v_or_b32_e32 v6, v6, v16
	v_lshl_add_u64 v[8:9], s[64:65], 0, v[6:7]
	v_lshl_add_u64 v[6:7], s[66:67], 0, v[6:7]
	v_mov_b32_e32 v13, v62
	v_mov_b32_e32 v14, v63
	v_mul_f32_e32 v6, v3, v21
	v_mul_f32_e32 v7, v2, v21
	v_fma_f32 v6, v2, v22, -v6
	v_fmac_f32_e32 v7, v3, v22
	v_cndmask_b32_e64 v6, -v7, v6, vcc
	v_bfe_u32 v7, v6, 16, 1
	v_add3_u32 v19, v6, v7, s80
	v_add_u32_e32 v6, 0x700, v4
	v_ashrrev_i32_e32 v20, 7, v6
	v_add_u32_e32 v6, s2, v20
	v_ashrrev_i32_e32 v7, 31, v6
	v_lshlrev_b64 v[6:7], 8, v[6:7]
	v_or_b32_e32 v6, v6, v16
	v_lshl_add_u64 v[8:9], s[64:65], 0, v[6:7]
	v_lshl_add_u64 v[6:7], s[66:67], 0, v[6:7]
	v_mov_b32_e32 v16, v64
	s_nop 0
	v_mov_b32_e32 v8, v65
	v_mad_i64_i32 v[6:7], s[0:1], v5, s68, v[0:1]
	v_lshl_add_u64 v[6:7], v[6:7], 0, s[78:79]
	v_lshl_add_u64 v[6:7], v[6:7], 0, v[192:193]
	v_add_co_u32_e64 v6, s[0:1], s4, v6
	v_mul_f32_e32 v5, v3, v25
	s_nop 0
	v_addc_co_u32_e64 v7, s[0:1], 0, v7, s[0:1]
	global_store_short_d16_hi v[6:7], v19, off offset:1024
	v_mul_f32_e32 v6, v2, v25
	v_fma_f32 v5, v2, v26, -v5
	v_fmac_f32_e32 v6, v3, v26
	v_cndmask_b32_e64 v5, -v6, v5, vcc
	v_bfe_u32 v6, v5, 16, 1
	v_add3_u32 v5, v5, v6, s80
	v_add_u32_e32 v6, s3, v23
	v_mad_i64_i32 v[6:7], s[0:1], v6, s68, v[0:1]
	v_lshl_add_u64 v[6:7], v[6:7], 0, s[78:79]
	v_lshl_add_u64 v[6:7], v[6:7], 0, v[192:193]
	v_add_co_u32_e64 v6, s[0:1], s4, v6
	s_nop 1
	v_addc_co_u32_e64 v7, s[0:1], 0, v7, s[0:1]
	global_store_short_d16_hi v[6:7], v5, off offset:1024
	v_mul_f32_e32 v5, v3, v11
	v_mul_f32_e32 v6, v2, v11
	v_fma_f32 v5, v2, v10, -v5
	v_fmac_f32_e32 v6, v3, v10
	v_cndmask_b32_e64 v5, -v6, v5, vcc
	v_bfe_u32 v6, v5, 16, 1
	v_add3_u32 v5, v5, v6, s80
	v_add_u32_e32 v6, s3, v24
	v_mad_i64_i32 v[6:7], s[0:1], v6, s68, v[0:1]
	v_lshl_add_u64 v[6:7], v[6:7], 0, s[78:79]
	v_lshl_add_u64 v[6:7], v[6:7], 0, v[192:193]
	v_add_co_u32_e64 v6, s[0:1], s4, v6
	s_nop 1
	v_addc_co_u32_e64 v7, s[0:1], 0, v7, s[0:1]
	global_store_short_d16_hi v[6:7], v5, off offset:1024
	v_mul_f32_e32 v5, v3, v17
	v_mul_f32_e32 v6, v2, v17
	v_fma_f32 v5, v2, v18, -v5
	v_fmac_f32_e32 v6, v3, v18
	v_cndmask_b32_e64 v5, -v6, v5, vcc
	v_bfe_u32 v6, v5, 16, 1
	v_add3_u32 v5, v5, v6, s80
	v_add_u32_e32 v6, s3, v15
	v_mad_i64_i32 v[6:7], s[0:1], v6, s68, v[0:1]
	v_lshl_add_u64 v[6:7], v[6:7], 0, s[78:79]
	v_lshl_add_u64 v[6:7], v[6:7], 0, v[192:193]
	v_add_co_u32_e64 v6, s[0:1], s4, v6
	s_nop 1
	v_addc_co_u32_e64 v7, s[0:1], 0, v7, s[0:1]
	global_store_short_d16_hi v[6:7], v5, off offset:1024
	v_mul_f32_e32 v5, v3, v13
	v_mul_f32_e32 v6, v2, v13
	v_fma_f32 v5, v2, v14, -v5
	v_fmac_f32_e32 v6, v3, v14
	v_cndmask_b32_e64 v5, -v6, v5, vcc
	v_bfe_u32 v6, v5, 16, 1
	v_add3_u32 v5, v5, v6, s80
	v_add_u32_e32 v6, s3, v12
	v_mad_i64_i32 v[6:7], s[0:1], v6, s68, v[0:1]
	v_lshl_add_u64 v[6:7], v[6:7], 0, s[78:79]
	v_lshl_add_u64 v[6:7], v[6:7], 0, v[192:193]
	v_add_co_u32_e64 v6, s[0:1], s4, v6
	s_nop 1
	v_addc_co_u32_e64 v7, s[0:1], 0, v7, s[0:1]
	global_store_short_d16_hi v[6:7], v5, off offset:1024
	v_mul_f32_e32 v5, v3, v16
	v_fma_f32 v5, v2, v8, -v5
	v_mul_f32_e32 v2, v2, v16
	v_fmac_f32_e32 v2, v3, v8
	v_cndmask_b32_e64 v2, -v2, v5, vcc
	v_bfe_u32 v3, v2, 16, 1
	v_add3_u32 v2, v2, v3, s80
	v_add_u32_e32 v3, s3, v20
	v_mad_i64_i32 v[0:1], s[0:1], v3, s68, v[0:1]
	v_lshl_add_u64 v[0:1], v[0:1], 0, s[78:79]
	v_lshl_add_u64 v[0:1], v[0:1], 0, v[192:193]
	v_add_co_u32_e32 v0, vcc, 0x1648000, v0
	s_nop 1
	v_addc_co_u32_e32 v1, vcc, 0, v1, vcc
	global_store_short_d16_hi v[0:1], v2, off offset:1024
	s_barrier
